# P0 weight-copy items: the 32 per-element gain loads issued together behind the weight loads and consumed with counted waits (was one load + wait-all per element)
# speedup vs baseline: 1.0184x; 1.0058x over previous
; #define LAS __attribute__((address_space(3)))
; __device__ __forceinline__ int srcmap(int mat, int r) {
;     ...
;     if (mat == 7) { const int tile = r >> 8, half = (r >> 7) & 1, within = r & 127; return half * DFF + tile * 128 + within; }
;     return r;
; }
; __device__ __forceinline__ void p0_item(const float* W, int ldw, const float* g, bf16* WT, int ldd, int row_off, int mat, bool split, LAS float* scr, int item, int nkb, int lane) {
;     const int rb = item / nkb, kb = item % nkb, k0 = 64 * kb, r0 = 32 * rb;
;     const int src = srcmap(mat, r0 + (lane & 31));
;     float wv[32];
;     const float* wp = W + (size_t)(k0 + (lane >> 5)) * ldw + (src >= 0 ? src : 0);
; #pragma unroll
;     for (int i = 0; i < 32; ++i) wv[i] = __builtin_nontemporal_load(wp + (size_t)(2 * i) * ldw);
.LBB0_43:
	s_andn2_b64 vcc, exec, s[2:3]
	s_cbranch_vccnz .LBB0_109
	v_readlane_b32 s2, v254, 34
	v_readlane_b32 s2, v254, 33
	s_add_i32 s2, s47, 0xf100
	s_bfe_i32 s48, s47, 0x10006
	s_and_b32 s48, s48, 0xb00
	s_and_b32 s2, s2, 0xff80
	s_and_b32 s3, s45, 0x60
	s_add_i32 s48, s48, s2
	s_or_b32 s2, s48, s3
	v_readlane_b32 s48, v254, 27
	s_waitcnt vmcnt(8)
	v_mbcnt_lo_u32_b32 v2, -1, 0
	v_mbcnt_hi_u32_b32 v2, -1, v2
	s_and_b32 s56, s31, 0x3c0
	v_and_b32_e32 v6, 31, v2
	v_ashrrev_i32_e32 v32, 5, v2
	v_readlane_b32 s50, v254, 29
	v_readlane_b32 s51, v254, 30
	s_waitcnt lgkmcnt(0)
	v_or_b32_e32 v1, s2, v6
	v_add_u32_e32 v0, s56, v32
	v_mov_b64_e32 v[4:5], s[50:51]
	s_movk_i32 s2, 0x5800
	v_mad_i64_i32 v[4:5], s[2:3], v0, s2, v[4:5]
	v_lshlrev_b32_e32 v64, 2, v1
	v_lshl_add_u64 v[4:5], v[4:5], 0, v[64:65]
	s_mov_b32 s2, 0xb000
	v_add_co_u32_e32 v8, vcc, s2, v4
	s_mov_b32 s2, 0x21000
	s_nop 0
	v_addc_co_u32_e32 v9, vcc, 0, v5, vcc
	v_add_co_u32_e32 v10, vcc, s75, v4
	v_readlane_b32 s50, v254, 31
	s_nop 0
	v_addc_co_u32_e32 v11, vcc, 0, v5, vcc
	v_add_co_u32_e32 v12, vcc, s2, v4
	s_mov_b32 s2, 0x37000
	s_nop 0
	v_addc_co_u32_e32 v13, vcc, 0, v5, vcc
	v_add_co_u32_e32 v14, vcc, s35, v4
	v_readlane_b32 s51, v254, 32
	s_nop 0
	v_addc_co_u32_e32 v15, vcc, 0, v5, vcc
	v_add_co_u32_e32 v16, vcc, s2, v4
	s_mov_b32 s2, 0x42000
	s_nop 0
	v_addc_co_u32_e32 v17, vcc, 0, v5, vcc
	v_add_co_u32_e32 v18, vcc, s2, v4
	s_mov_b32 s2, 0x4d000
	s_nop 0
	v_addc_co_u32_e32 v19, vcc, 0, v5, vcc
	v_add_co_u32_e32 v20, vcc, s2, v4
	s_mov_b32 s2, 0x58000
	s_nop 0
	v_addc_co_u32_e32 v21, vcc, 0, v5, vcc
	global_load_dword v36, v[4:5], off nt
	global_load_dword v35, v[8:9], off nt
	global_load_dword v34, v[10:11], off nt
	global_load_dword v33, v[12:13], off nt
	global_load_dword v31, v[14:15], off nt
	global_load_dword v29, v[16:17], off nt
	global_load_dword v27, v[18:19], off nt
	global_load_dword v25, v[20:21], off nt
	v_add_co_u32_e32 v8, vcc, s2, v4
	s_mov_b32 s2, 0x63000
	s_nop 0
	v_addc_co_u32_e32 v9, vcc, 0, v5, vcc
	v_add_co_u32_e32 v10, vcc, s2, v4
	s_mov_b32 s2, 0x6e000
	s_nop 0
	v_addc_co_u32_e32 v11, vcc, 0, v5, vcc
	v_add_co_u32_e32 v12, vcc, s2, v4
	s_mov_b32 s2, 0x79000
	s_nop 0
	v_addc_co_u32_e32 v13, vcc, 0, v5, vcc
	v_add_co_u32_e32 v14, vcc, s2, v4
	s_mov_b32 s2, 0x84000
	s_nop 0
	v_addc_co_u32_e32 v15, vcc, 0, v5, vcc
	v_add_co_u32_e32 v16, vcc, s2, v4
	s_mov_b32 s2, 0x8f000
	s_nop 0
	v_addc_co_u32_e32 v17, vcc, 0, v5, vcc
	v_add_co_u32_e32 v18, vcc, s2, v4
	s_mov_b32 s2, 0x9a000
	s_nop 0
	v_addc_co_u32_e32 v19, vcc, 0, v5, vcc
	v_add_co_u32_e32 v38, vcc, s2, v4
	s_mov_b32 s2, 0xa5000
	s_nop 0
	v_addc_co_u32_e32 v39, vcc, 0, v5, vcc
	v_add_co_u32_e32 v40, vcc, s2, v4
	s_mov_b32 s2, 0xb0000
	s_nop 0
	v_addc_co_u32_e32 v41, vcc, 0, v5, vcc
	global_load_dword v30, v[8:9], off nt
	global_load_dword v28, v[10:11], off nt
	global_load_dword v26, v[12:13], off nt
	global_load_dword v24, v[14:15], off nt
	global_load_dword v23, v[16:17], off nt
	global_load_dword v21, v[18:19], off nt
	s_nop 0
	global_load_dword v19, v[38:39], off nt
	global_load_dword v17, v[40:41], off nt
	v_add_co_u32_e32 v8, vcc, s2, v4
	s_mov_b32 s2, 0xbb000
	s_nop 0
	v_addc_co_u32_e32 v9, vcc, 0, v5, vcc
	v_add_co_u32_e32 v10, vcc, s2, v4
	s_mov_b32 s2, 0xc6000
	s_nop 0
	v_addc_co_u32_e32 v11, vcc, 0, v5, vcc
	v_add_co_u32_e32 v12, vcc, s2, v4
	s_mov_b32 s2, 0xd1000
	s_nop 0
	v_addc_co_u32_e32 v13, vcc, 0, v5, vcc
	v_add_co_u32_e32 v14, vcc, s2, v4
	s_mov_b32 s2, 0xdc000
	s_nop 0
	v_addc_co_u32_e32 v15, vcc, 0, v5, vcc
	v_add_co_u32_e32 v38, vcc, s2, v4
	s_mov_b32 s2, 0xe7000
	s_nop 0
	v_addc_co_u32_e32 v39, vcc, 0, v5, vcc
	v_add_co_u32_e32 v40, vcc, s2, v4
	s_mov_b32 s2, 0xf2000
	s_nop 0
	v_addc_co_u32_e32 v41, vcc, 0, v5, vcc
	v_add_co_u32_e32 v42, vcc, s2, v4
	s_mov_b32 s2, 0xfd000
	s_nop 0
	v_addc_co_u32_e32 v43, vcc, 0, v5, vcc
	v_add_co_u32_e32 v44, vcc, s2, v4
	s_mov_b32 s2, 0x108000
	s_nop 0
	v_addc_co_u32_e32 v45, vcc, 0, v5, vcc
	global_load_dword v22, v[8:9], off nt
	global_load_dword v20, v[10:11], off nt
	global_load_dword v18, v[12:13], off nt
	global_load_dword v16, v[14:15], off nt
	s_nop 0
	global_load_dword v14, v[38:39], off nt
	global_load_dword v12, v[40:41], off nt
	global_load_dword v10, v[42:43], off nt
	global_load_dword v8, v[44:45], off nt
	v_add_co_u32_e32 v38, vcc, s2, v4
	s_mov_b32 s2, 0x113000
	s_nop 0
	v_addc_co_u32_e32 v39, vcc, 0, v5, vcc
	v_add_co_u32_e32 v40, vcc, s2, v4
	s_mov_b32 s2, 0x11e000
	s_nop 0
	v_addc_co_u32_e32 v41, vcc, 0, v5, vcc
	v_add_co_u32_e32 v42, vcc, s2, v4
	s_mov_b32 s2, 0x129000
	s_nop 0
	v_addc_co_u32_e32 v43, vcc, 0, v5, vcc
	v_add_co_u32_e32 v44, vcc, s2, v4
	s_mov_b32 s2, 0x134000
	s_nop 0
	v_addc_co_u32_e32 v45, vcc, 0, v5, vcc
	v_add_co_u32_e32 v46, vcc, s2, v4
	v_readlane_b32 s49, v254, 28
	s_nop 0
	v_addc_co_u32_e32 v47, vcc, 0, v5, vcc
	v_add_co_u32_e32 v48, vcc, 0x13f000, v4
	v_ashrrev_i32_e32 v1, 31, v0
	s_nop 0
	v_addc_co_u32_e32 v49, vcc, 0, v5, vcc
	v_add_co_u32_e32 v50, vcc, 0x14a000, v4
	v_cndmask_b32_e64 v37, 0, 1, s[50:51]
	s_nop 0
	v_addc_co_u32_e32 v51, vcc, 0, v5, vcc
	v_add_co_u32_e32 v52, vcc, 0x155000, v4
	v_cmp_ne_u32_e64 s[2:3], 1, v37
	s_nop 0
	v_addc_co_u32_e32 v53, vcc, 0, v5, vcc
	global_load_dword v15, v[38:39], off nt
	global_load_dword v13, v[40:41], off nt
	global_load_dword v11, v[42:43], off nt
	global_load_dword v9, v[44:45], off nt
	global_load_dword v7, v[46:47], off nt
	global_load_dword v5, v[48:49], off nt
	global_load_dword v4, v[50:51], off nt
	global_load_dword v3, v[52:53], off nt
	s_andn2_b64 vcc, exec, s[50:51]
	v_lshl_add_u64 v[0:1], v[0:1], 2, s[48:49]
	s_cbranch_vccnz .Lp0g_0
; __device__ __forceinline__ void p0_item(const float* W, int ldw, const float* g, bf16* WT, int ldd, int row_off, int mat, bool split, LAS float* scr, int item, int nkb, int lane) {
;     ...
;     const float gz = src >= 0 ? 1.f : 0.f;
; #pragma unroll
;     for (int i = 0; i < 32; ++i) { const int kk = 2 * i + (lane >> 5);
;         float v = wv[i] * gz; if (g) v *= g[k0 + kk];
;         scr[kk * 33 + (lane & 31)] = v; }
	global_load_dword v56, v[0:1], off
	global_load_dword v57, v[0:1], off offset:8
	global_load_dword v58, v[0:1], off offset:16
	global_load_dword v59, v[0:1], off offset:24
	global_load_dword v60, v[0:1], off offset:32
	global_load_dword v61, v[0:1], off offset:40
	global_load_dword v62, v[0:1], off offset:48
	global_load_dword v63, v[0:1], off offset:56
	global_load_dword v78, v[0:1], off offset:64
	global_load_dword v79, v[0:1], off offset:72
	global_load_dword v80, v[0:1], off offset:80
	global_load_dword v81, v[0:1], off offset:88
	global_load_dword v82, v[0:1], off offset:96
	global_load_dword v83, v[0:1], off offset:104
	global_load_dword v84, v[0:1], off offset:112
	global_load_dword v85, v[0:1], off offset:120
	global_load_dword v98, v[0:1], off offset:128
	global_load_dword v103, v[0:1], off offset:136
	global_load_dword v134, v[0:1], off offset:144
	global_load_dword v135, v[0:1], off offset:152
	global_load_dword v136, v[0:1], off offset:160
	global_load_dword v137, v[0:1], off offset:168
	global_load_dword v204, v[0:1], off offset:176
	global_load_dword v205, v[0:1], off offset:184
	global_load_dword v206, v[0:1], off offset:192
	global_load_dword v207, v[0:1], off offset:200
	global_load_dword v208, v[0:1], off offset:208
	global_load_dword v209, v[0:1], off offset:216
	global_load_dword v210, v[0:1], off offset:224
	global_load_dword v211, v[0:1], off offset:232
	global_load_dword v212, v[0:1], off offset:240
	global_load_dword v213, v[0:1], off offset:248
.Lp0g_0:
	s_cbranch_vccnz .LBB0_46
	s_waitcnt vmcnt(31)
	v_mul_f32_e32 v36, v36, v56
.LBB0_46:
	v_lshl_add_u32 v6, v6, 2, s28
	v_mul_lo_u32 v32, v32, s26
	v_add_u32_e32 v6, v6, v32
	s_and_b64 vcc, exec, s[2:3]
	s_waitcnt vmcnt(31)
	ds_write_b32 v6, v36
	s_cbranch_vccnz .LBB0_48
	s_waitcnt vmcnt(30)
	v_mul_f32_e32 v35, v35, v57
.LBB0_48:
	s_and_b64 vcc, exec, s[2:3]
	s_waitcnt vmcnt(30)
	ds_write_b32 v6, v35 offset:264
	s_cbranch_vccnz .LBB0_50
	s_waitcnt vmcnt(29)
	v_mul_f32_e32 v34, v34, v58
.LBB0_50:
	s_and_b64 vcc, exec, s[2:3]
	s_waitcnt vmcnt(29)
	ds_write_b32 v6, v34 offset:528
	s_cbranch_vccnz .LBB0_52
	s_waitcnt vmcnt(28)
	v_mul_f32_e32 v33, v33, v59
.LBB0_52:
	s_and_b64 vcc, exec, s[2:3]
	s_waitcnt vmcnt(28)
	ds_write_b32 v6, v33 offset:792
	s_cbranch_vccnz .LBB0_54
	s_waitcnt vmcnt(27)
	v_mul_f32_e32 v31, v31, v60
.LBB0_54:
	s_and_b64 vcc, exec, s[2:3]
	s_waitcnt vmcnt(27)
	ds_write_b32 v6, v31 offset:1056
	s_cbranch_vccnz .LBB0_56
	s_waitcnt vmcnt(26)
	v_mul_f32_e32 v29, v29, v61
.LBB0_56:
	s_and_b64 vcc, exec, s[2:3]
	s_waitcnt vmcnt(26)
	ds_write_b32 v6, v29 offset:1320
	s_cbranch_vccnz .LBB0_58
	s_waitcnt vmcnt(25)
	v_mul_f32_e32 v27, v27, v62
.LBB0_58:
	s_and_b64 vcc, exec, s[2:3]
	s_waitcnt vmcnt(25)
	ds_write_b32 v6, v27 offset:1584
	s_cbranch_vccnz .LBB0_60
	s_waitcnt vmcnt(24)
	v_mul_f32_e32 v25, v25, v63
.LBB0_60:
	s_and_b64 vcc, exec, s[2:3]
	s_waitcnt vmcnt(24)
	ds_write_b32 v6, v25 offset:1848
	s_cbranch_vccnz .LBB0_62
	s_waitcnt vmcnt(23)
	v_mul_f32_e32 v30, v30, v78
.LBB0_62:
	s_and_b64 vcc, exec, s[2:3]
	s_waitcnt vmcnt(23)
	ds_write_b32 v6, v30 offset:2112
	s_cbranch_vccnz .LBB0_64
	s_waitcnt vmcnt(22)
	v_mul_f32_e32 v28, v28, v79
.LBB0_64:
	s_and_b64 vcc, exec, s[2:3]
	s_waitcnt vmcnt(22)
	ds_write_b32 v6, v28 offset:2376
	s_cbranch_vccnz .LBB0_66
	s_waitcnt vmcnt(21)
	v_mul_f32_e32 v26, v26, v80
.LBB0_66:
	s_and_b64 vcc, exec, s[2:3]
	s_waitcnt vmcnt(21)
	ds_write_b32 v6, v26 offset:2640
	s_cbranch_vccnz .LBB0_68
	s_waitcnt vmcnt(20)
	v_mul_f32_e32 v24, v24, v81
.LBB0_68:
	s_and_b64 vcc, exec, s[2:3]
	s_waitcnt vmcnt(20)
	ds_write_b32 v6, v24 offset:2904
	s_cbranch_vccnz .LBB0_70
	s_waitcnt vmcnt(19)
	v_mul_f32_e32 v23, v23, v82
.LBB0_70:
	s_and_b64 vcc, exec, s[2:3]
	s_waitcnt vmcnt(19)
	ds_write_b32 v6, v23 offset:3168
	s_cbranch_vccnz .LBB0_72
	s_waitcnt vmcnt(18)
	v_mul_f32_e32 v21, v21, v83
.LBB0_72:
	s_and_b64 vcc, exec, s[2:3]
	s_waitcnt vmcnt(18)
	ds_write_b32 v6, v21 offset:3432
	s_cbranch_vccnz .LBB0_74
	s_waitcnt vmcnt(17)
	v_mul_f32_e32 v19, v19, v84
.LBB0_74:
	s_and_b64 vcc, exec, s[2:3]
	s_waitcnt vmcnt(17)
	ds_write_b32 v6, v19 offset:3696
	s_cbranch_vccnz .LBB0_76
	s_waitcnt vmcnt(16)
	v_mul_f32_e32 v17, v17, v85
.LBB0_76:
	s_and_b64 vcc, exec, s[2:3]
	s_waitcnt vmcnt(16)
	ds_write_b32 v6, v17 offset:3960
	s_cbranch_vccnz .LBB0_78
	s_waitcnt vmcnt(15)
	v_mul_f32_e32 v22, v22, v98
.LBB0_78:
	s_and_b64 vcc, exec, s[2:3]
	s_waitcnt vmcnt(15)
	ds_write_b32 v6, v22 offset:4224
	s_cbranch_vccnz .LBB0_80
	s_waitcnt vmcnt(14)
	v_mul_f32_e32 v20, v20, v103
.LBB0_80:
	s_and_b64 vcc, exec, s[2:3]
	s_waitcnt vmcnt(14)
	ds_write_b32 v6, v20 offset:4488
	s_cbranch_vccnz .LBB0_82
	s_waitcnt vmcnt(13)
	v_mul_f32_e32 v18, v18, v134
.LBB0_82:
	s_and_b64 vcc, exec, s[2:3]
	s_waitcnt vmcnt(13)
	ds_write_b32 v6, v18 offset:4752
	s_cbranch_vccnz .LBB0_84
	s_waitcnt vmcnt(12)
	v_mul_f32_e32 v16, v16, v135
.LBB0_84:
	s_and_b64 vcc, exec, s[2:3]
	s_waitcnt vmcnt(12)
	ds_write_b32 v6, v16 offset:5016
	s_cbranch_vccnz .LBB0_86
	s_waitcnt vmcnt(11)
	v_mul_f32_e32 v14, v14, v136
.LBB0_86:
	s_and_b64 vcc, exec, s[2:3]
	s_waitcnt vmcnt(11)
	ds_write_b32 v6, v14 offset:5280
	s_cbranch_vccnz .LBB0_88
	s_waitcnt vmcnt(10)
	v_mul_f32_e32 v12, v12, v137
.LBB0_88:
	s_and_b64 vcc, exec, s[2:3]
	s_waitcnt vmcnt(10)
	ds_write_b32 v6, v12 offset:5544
	s_cbranch_vccnz .LBB0_90
	s_waitcnt vmcnt(9)
	v_mul_f32_e32 v10, v10, v204
.LBB0_90:
	s_and_b64 vcc, exec, s[2:3]
	s_waitcnt vmcnt(9)
	ds_write_b32 v6, v10 offset:5808
	s_cbranch_vccnz .LBB0_92
	s_waitcnt vmcnt(8)
	v_mul_f32_e32 v8, v8, v205
.LBB0_92:
	s_and_b64 vcc, exec, s[2:3]
	s_waitcnt vmcnt(8)
	ds_write_b32 v6, v8 offset:6072
	s_cbranch_vccnz .LBB0_94
	s_waitcnt vmcnt(7)
	v_mul_f32_e32 v15, v15, v206
.LBB0_94:
	s_and_b64 vcc, exec, s[2:3]
	s_waitcnt vmcnt(7)
	ds_write_b32 v6, v15 offset:6336
	s_cbranch_vccnz .LBB0_96
	s_waitcnt vmcnt(6)
	v_mul_f32_e32 v13, v13, v207
.LBB0_96:
	s_and_b64 vcc, exec, s[2:3]
	s_waitcnt vmcnt(6)
	ds_write_b32 v6, v13 offset:6600
	s_cbranch_vccnz .LBB0_98
	s_waitcnt vmcnt(5)
	v_mul_f32_e32 v11, v11, v208
.LBB0_98:
	s_and_b64 vcc, exec, s[2:3]
	s_waitcnt vmcnt(5)
	ds_write_b32 v6, v11 offset:6864
	s_cbranch_vccnz .LBB0_100
	s_waitcnt vmcnt(4)
	v_mul_f32_e32 v9, v9, v209
.LBB0_100:
	s_and_b64 vcc, exec, s[2:3]
	s_waitcnt vmcnt(4)
	ds_write_b32 v6, v9 offset:7128
	s_cbranch_vccnz .LBB0_102
	s_waitcnt vmcnt(3)
	v_mul_f32_e32 v7, v7, v210
.LBB0_102:
	s_and_b64 vcc, exec, s[2:3]
	s_waitcnt vmcnt(3)
	ds_write_b32 v6, v7 offset:7392
	s_cbranch_vccnz .LBB0_104
	s_waitcnt vmcnt(2)
	v_mul_f32_e32 v5, v5, v211
.LBB0_104:
	s_and_b64 vcc, exec, s[2:3]
	s_waitcnt vmcnt(2)
	ds_write_b32 v6, v5 offset:7656
	s_cbranch_vccnz .LBB0_106
	s_waitcnt vmcnt(1)
	v_mul_f32_e32 v4, v4, v212
.LBB0_106:
	s_and_b64 vcc, exec, s[2:3]
	s_waitcnt vmcnt(1)
	ds_write_b32 v6, v4 offset:7920
	s_cbranch_vccnz .LBB0_108
	s_waitcnt vmcnt(0)
	v_mul_f32_e32 v3, v3, v213

; __device__ __forceinline__ void p0_item(const float* W, int ldw, const float* g, bf16* WT, int ldd, int row_off, int mat, bool split, LAS float* scr, int item, int nkb, int lane) {
;     const int rb = item / nkb, kb = item % nkb, k0 = 64 * kb, r0 = 32 * rb;
;     const int src = srcmap(mat, r0 + (lane & 31));
;     float wv[32];
;     const float* wp = W + (size_t)(k0 + (lane >> 5)) * ldw + (src >= 0 ? src : 0);
; #pragma unroll
;     for (int i = 0; i < 32; ++i) wv[i] = __builtin_nontemporal_load(wp + (size_t)(2 * i) * ldw);
;     const float gz = src >= 0 ? 1.f : 0.f;
; #pragma unroll
;     for (int i = 0; i < 32; ++i) { const int kk = 2 * i + (lane >> 5);
;         float v = wv[i] * gz; if (g) v *= g[k0 + kk];
;         scr[kk * 33 + (lane & 31)] = v; }
.LBB0_113:
	s_andn2_b64 vcc, exec, s[2:3]
	s_cbranch_vccnz .LBB0_179
	s_waitcnt vmcnt(9)
	v_mbcnt_lo_u32_b32 v4, -1, 0
	v_mbcnt_hi_u32_b32 v4, -1, v4
	s_and_b32 s56, s31, 0x3c0
	v_ashrrev_i32_e32 v27, 5, v4
	s_add_i32 s2, s45, 0x800
	s_waitcnt vmcnt(8)
	v_add_u32_e32 v0, s56, v27
	s_and_b32 s57, s2, 0x1ffe0
	v_and_b32_e32 v5, 31, v4
	s_waitcnt lgkmcnt(0)
	v_ashrrev_i32_e32 v1, 31, v0
	v_readlane_b32 s48, v254, 59
	v_or_b32_e32 v6, s57, v5
	v_lshlrev_b64 v[2:3], 12, v[0:1]
	v_readlane_b32 s50, v254, 61
	v_readlane_b32 s51, v254, 62
	v_lshlrev_b32_e32 v64, 2, v6
	s_movk_i32 s2, 0x2000
	v_lshl_add_u64 v[2:3], s[50:51], 0, v[2:3]
	v_lshl_add_u64 v[2:3], v[2:3], 0, v[64:65]
	v_add_co_u32_e32 v6, vcc, s2, v2
	s_movk_i32 s2, 0x4000
	s_nop 0
	v_addc_co_u32_e32 v7, vcc, 0, v3, vcc
	v_add_co_u32_e32 v8, vcc, s2, v2
	s_movk_i32 s2, 0x6000
	s_nop 0
	v_addc_co_u32_e32 v9, vcc, 0, v3, vcc
	v_add_co_u32_e32 v10, vcc, s2, v2
	s_mov_b32 s2, 0x8000
	s_nop 0
	v_addc_co_u32_e32 v11, vcc, 0, v3, vcc
	v_add_co_u32_e32 v12, vcc, s2, v2
	s_mov_b32 s2, 0xa000
	s_nop 0
	v_addc_co_u32_e32 v13, vcc, 0, v3, vcc
	v_add_co_u32_e32 v14, vcc, s2, v2
	s_mov_b32 s2, 0xc000
	s_nop 0
	v_addc_co_u32_e32 v15, vcc, 0, v3, vcc
	v_add_co_u32_e32 v16, vcc, s2, v2
	s_mov_b32 s2, 0xe000
	s_nop 0
	v_addc_co_u32_e32 v17, vcc, 0, v3, vcc
	v_add_co_u32_e32 v18, vcc, s2, v2
	s_mov_b32 s2, 0x10000
	s_nop 0
	v_addc_co_u32_e32 v19, vcc, 0, v3, vcc
	global_load_dword v36, v[2:3], off nt
	global_load_dword v35, v[6:7], off nt
	global_load_dword v34, v[8:9], off nt
	global_load_dword v32, v[10:11], off nt
	global_load_dword v30, v[12:13], off nt
	global_load_dword v28, v[14:15], off nt
	global_load_dword v24, v[16:17], off nt
	global_load_dword v21, v[18:19], off nt
	v_add_co_u32_e32 v6, vcc, s2, v2
	s_mov_b32 s2, 0x12000
	s_nop 0
	v_addc_co_u32_e32 v7, vcc, 0, v3, vcc
	v_add_co_u32_e32 v8, vcc, s2, v2
	s_mov_b32 s2, 0x14000
	s_nop 0
	v_addc_co_u32_e32 v9, vcc, 0, v3, vcc
	v_add_co_u32_e32 v10, vcc, s2, v2
	s_mov_b32 s2, 0x18000
	s_nop 0
	v_addc_co_u32_e32 v11, vcc, 0, v3, vcc
	v_add_co_u32_e32 v12, vcc, s75, v2
	v_readlane_b32 s49, v254, 60
	s_nop 0
	v_addc_co_u32_e32 v13, vcc, 0, v3, vcc
	v_add_co_u32_e32 v14, vcc, s2, v2
	s_mov_b32 s2, 0x1a000
	s_nop 0
	v_addc_co_u32_e32 v15, vcc, 0, v3, vcc
	v_add_co_u32_e32 v16, vcc, s2, v2
	s_mov_b32 s2, 0x1c000
	s_nop 0
	v_addc_co_u32_e32 v17, vcc, 0, v3, vcc
	v_add_co_u32_e32 v38, vcc, s2, v2
	s_mov_b32 s2, 0x1e000
	s_nop 0
	v_addc_co_u32_e32 v39, vcc, 0, v3, vcc
	v_add_co_u32_e32 v40, vcc, s2, v2
	s_mov_b32 s2, 0x20000
	s_nop 0
	v_addc_co_u32_e32 v41, vcc, 0, v3, vcc
	global_load_dword v33, v[6:7], off nt
	global_load_dword v31, v[8:9], off nt
	global_load_dword v29, v[10:11], off nt
	global_load_dword v25, v[12:13], off nt
	global_load_dword v22, v[14:15], off nt
	global_load_dword v19, v[16:17], off nt
	s_nop 0
	global_load_dword v17, v[38:39], off nt
	global_load_dword v14, v[40:41], off nt
	v_add_co_u32_e32 v6, vcc, s2, v2
	s_mov_b32 s2, 0x22000
	s_nop 0
	v_addc_co_u32_e32 v7, vcc, 0, v3, vcc
	v_add_co_u32_e32 v8, vcc, s2, v2
	s_mov_b32 s2, 0x24000
	s_nop 0
	v_addc_co_u32_e32 v9, vcc, 0, v3, vcc
	v_add_co_u32_e32 v10, vcc, s2, v2
	s_mov_b32 s2, 0x26000
	s_nop 0
	v_addc_co_u32_e32 v11, vcc, 0, v3, vcc
	v_add_co_u32_e32 v12, vcc, s2, v2
	s_mov_b32 s2, 0x28000
	s_nop 0
	v_addc_co_u32_e32 v13, vcc, 0, v3, vcc
	v_add_co_u32_e32 v38, vcc, s2, v2
	s_mov_b32 s2, 0x2a000
	s_nop 0
	v_addc_co_u32_e32 v39, vcc, 0, v3, vcc
	v_add_co_u32_e32 v40, vcc, s2, v2
	s_mov_b32 s2, 0x2e000
	s_nop 0
	v_addc_co_u32_e32 v41, vcc, 0, v3, vcc
	v_add_co_u32_e32 v42, vcc, s35, v2
	v_readlane_b32 s48, v254, 37
	s_nop 0
	v_addc_co_u32_e32 v43, vcc, 0, v3, vcc
	v_add_co_u32_e32 v44, vcc, s2, v2
	s_mov_b32 s2, 0x30000
	s_nop 0
	v_addc_co_u32_e32 v45, vcc, 0, v3, vcc
	global_load_dword v26, v[6:7], off nt
	global_load_dword v23, v[8:9], off nt
	global_load_dword v20, v[10:11], off nt
	global_load_dword v18, v[12:13], off nt
	global_load_dword v15, v[38:39], off nt
	s_nop 0
	global_load_dword v12, v[40:41], off nt
	global_load_dword v10, v[42:43], off nt
	global_load_dword v8, v[44:45], off nt
	v_add_co_u32_e32 v6, vcc, s2, v2
	s_mov_b32 s2, 0x32000
	s_nop 0
	v_addc_co_u32_e32 v7, vcc, 0, v3, vcc
	v_add_co_u32_e32 v38, vcc, s2, v2
	v_readlane_b32 s49, v254, 38
	s_nop 0
	v_addc_co_u32_e32 v39, vcc, 0, v3, vcc
	v_add_co_u32_e32 v40, vcc, s97, v2
	v_cndmask_b32_e64 v37, 0, 1, s[48:49]
	s_nop 0
	v_addc_co_u32_e32 v41, vcc, 0, v3, vcc
	v_add_co_u32_e32 v42, vcc, s74, v2
	v_cmp_ne_u32_e64 s[2:3], 1, v37
	s_nop 0
	v_addc_co_u32_e32 v43, vcc, 0, v3, vcc
	v_add_co_u32_e32 v44, vcc, s96, v2
	v_lshl_add_u64 v[0:1], v[0:1], 2, s[16:17]
	s_nop 0
	v_addc_co_u32_e32 v45, vcc, 0, v3, vcc
	v_add_co_u32_e32 v46, vcc, 0x3a000, v2
	s_nop 1
	v_addc_co_u32_e32 v47, vcc, 0, v3, vcc
	v_add_co_u32_e32 v48, vcc, 0x3c000, v2
	s_nop 1
	v_addc_co_u32_e32 v49, vcc, 0, v3, vcc
	v_add_co_u32_e32 v50, vcc, 0x3e000, v2
	s_nop 1
	v_addc_co_u32_e32 v51, vcc, 0, v3, vcc
	global_load_dword v16, v[6:7], off nt
	global_load_dword v13, v[38:39], off nt
	global_load_dword v11, v[40:41], off nt
	global_load_dword v9, v[42:43], off nt
	s_nop 0
	global_load_dword v7, v[44:45], off nt
	global_load_dword v6, v[46:47], off nt
	global_load_dword v3, v[48:49], off nt
	global_load_dword v2, v[50:51], off nt
	s_andn2_b64 vcc, exec, s[48:49]
	s_cbranch_vccnz .Lp0g_1
	global_load_dword v56, v[0:1], off
	global_load_dword v57, v[0:1], off offset:8
	global_load_dword v58, v[0:1], off offset:16
	global_load_dword v59, v[0:1], off offset:24
	global_load_dword v60, v[0:1], off offset:32
	global_load_dword v61, v[0:1], off offset:40
	global_load_dword v62, v[0:1], off offset:48
	global_load_dword v63, v[0:1], off offset:56
	global_load_dword v78, v[0:1], off offset:64
	global_load_dword v79, v[0:1], off offset:72
	global_load_dword v80, v[0:1], off offset:80
	global_load_dword v81, v[0:1], off offset:88
	global_load_dword v82, v[0:1], off offset:96
	global_load_dword v83, v[0:1], off offset:104
	global_load_dword v84, v[0:1], off offset:112
	global_load_dword v85, v[0:1], off offset:120
	global_load_dword v98, v[0:1], off offset:128
	global_load_dword v103, v[0:1], off offset:136
	global_load_dword v134, v[0:1], off offset:144
	global_load_dword v135, v[0:1], off offset:152
	global_load_dword v136, v[0:1], off offset:160
	global_load_dword v137, v[0:1], off offset:168
	global_load_dword v204, v[0:1], off offset:176
	global_load_dword v205, v[0:1], off offset:184
	global_load_dword v206, v[0:1], off offset:192
	global_load_dword v207, v[0:1], off offset:200
	global_load_dword v208, v[0:1], off offset:208
	global_load_dword v209, v[0:1], off offset:216
	global_load_dword v210, v[0:1], off offset:224
	global_load_dword v211, v[0:1], off offset:232
	global_load_dword v212, v[0:1], off offset:240
	global_load_dword v213, v[0:1], off offset:248

; __device__ __forceinline__ void p0_item(const float* W, int ldw, const float* g, bf16* WT, int ldd, int row_off, int mat, bool split, LAS float* scr, int item, int nkb, int lane) {
;     ...
;     const float gz = src >= 0 ? 1.f : 0.f;
; #pragma unroll
;     for (int i = 0; i < 32; ++i) { const int kk = 2 * i + (lane >> 5);
;         float v = wv[i] * gz; if (g) v *= g[k0 + kk];
;         scr[kk * 33 + (lane & 31)] = v; }
.LBB0_116:
	v_lshl_add_u32 v5, v5, 2, s28
	v_mul_lo_u32 v27, v27, s26
	v_add_u32_e32 v5, v5, v27
	s_and_b64 vcc, exec, s[2:3]
	s_waitcnt vmcnt(31)
	ds_write_b32 v5, v36
	s_cbranch_vccnz .LBB0_118
	s_waitcnt vmcnt(30)
	v_mul_f32_e32 v35, v35, v57
.LBB0_118:
	s_and_b64 vcc, exec, s[2:3]
	s_waitcnt vmcnt(30)
	ds_write_b32 v5, v35 offset:264
	s_cbranch_vccnz .LBB0_120
	s_waitcnt vmcnt(29)
	v_mul_f32_e32 v34, v34, v58
.LBB0_120:
	s_and_b64 vcc, exec, s[2:3]
	s_waitcnt vmcnt(29)
	ds_write_b32 v5, v34 offset:528
	s_cbranch_vccnz .LBB0_122
	s_waitcnt vmcnt(28)
	v_mul_f32_e32 v32, v32, v59
.LBB0_122:
	s_and_b64 vcc, exec, s[2:3]
	s_waitcnt vmcnt(28)
	ds_write_b32 v5, v32 offset:792
	s_cbranch_vccnz .LBB0_124
	s_waitcnt vmcnt(27)
	v_mul_f32_e32 v30, v30, v60
.LBB0_124:
	s_and_b64 vcc, exec, s[2:3]
	s_waitcnt vmcnt(27)
	ds_write_b32 v5, v30 offset:1056
	s_cbranch_vccnz .LBB0_126
	s_waitcnt vmcnt(26)
	v_mul_f32_e32 v28, v28, v61
.LBB0_126:
	s_and_b64 vcc, exec, s[2:3]
	s_waitcnt vmcnt(26)
	ds_write_b32 v5, v28 offset:1320
	s_cbranch_vccnz .LBB0_128
	s_waitcnt vmcnt(25)
	v_mul_f32_e32 v24, v24, v62
.LBB0_128:
	s_and_b64 vcc, exec, s[2:3]
	s_waitcnt vmcnt(25)
	ds_write_b32 v5, v24 offset:1584
	s_cbranch_vccnz .LBB0_130
	s_waitcnt vmcnt(24)
	v_mul_f32_e32 v21, v21, v63
.LBB0_130:
	s_and_b64 vcc, exec, s[2:3]
	s_waitcnt vmcnt(24)
	ds_write_b32 v5, v21 offset:1848
	s_cbranch_vccnz .LBB0_132
	s_waitcnt vmcnt(23)
	v_mul_f32_e32 v33, v33, v78
.LBB0_132:
	s_and_b64 vcc, exec, s[2:3]
	s_waitcnt vmcnt(23)
	ds_write_b32 v5, v33 offset:2112
	s_cbranch_vccnz .LBB0_134
	s_waitcnt vmcnt(22)
	v_mul_f32_e32 v31, v31, v79
.LBB0_134:
	s_and_b64 vcc, exec, s[2:3]
	s_waitcnt vmcnt(22)
	ds_write_b32 v5, v31 offset:2376
	s_cbranch_vccnz .LBB0_136
	s_waitcnt vmcnt(21)
	v_mul_f32_e32 v29, v29, v80
.LBB0_136:
	s_and_b64 vcc, exec, s[2:3]
	s_waitcnt vmcnt(21)
	ds_write_b32 v5, v29 offset:2640
	s_cbranch_vccnz .LBB0_138
	s_waitcnt vmcnt(20)
	v_mul_f32_e32 v25, v25, v81
.LBB0_138:
	s_and_b64 vcc, exec, s[2:3]
	s_waitcnt vmcnt(20)
	ds_write_b32 v5, v25 offset:2904
	s_cbranch_vccnz .LBB0_140
	s_waitcnt vmcnt(19)
	v_mul_f32_e32 v22, v22, v82
.LBB0_140:
	s_and_b64 vcc, exec, s[2:3]
	s_waitcnt vmcnt(19)
	ds_write_b32 v5, v22 offset:3168
	s_cbranch_vccnz .LBB0_142
	s_waitcnt vmcnt(18)
	v_mul_f32_e32 v19, v19, v83
.LBB0_142:
	s_and_b64 vcc, exec, s[2:3]
	s_waitcnt vmcnt(18)
	ds_write_b32 v5, v19 offset:3432
	s_cbranch_vccnz .LBB0_144
	s_waitcnt vmcnt(17)
	v_mul_f32_e32 v17, v17, v84
.LBB0_144:
	s_and_b64 vcc, exec, s[2:3]
	s_waitcnt vmcnt(17)
	ds_write_b32 v5, v17 offset:3696
	s_cbranch_vccnz .LBB0_146
	s_waitcnt vmcnt(16)
	v_mul_f32_e32 v14, v14, v85
.LBB0_146:
	s_and_b64 vcc, exec, s[2:3]
	s_waitcnt vmcnt(16)
	ds_write_b32 v5, v14 offset:3960
	s_cbranch_vccnz .LBB0_148
	s_waitcnt vmcnt(15)
	v_mul_f32_e32 v26, v26, v98
.LBB0_148:
	s_and_b64 vcc, exec, s[2:3]
	s_waitcnt vmcnt(15)
	ds_write_b32 v5, v26 offset:4224
	s_cbranch_vccnz .LBB0_150
	s_waitcnt vmcnt(14)
	v_mul_f32_e32 v23, v23, v103
.LBB0_150:
	s_and_b64 vcc, exec, s[2:3]
	s_waitcnt vmcnt(14)
	ds_write_b32 v5, v23 offset:4488
	s_cbranch_vccnz .LBB0_152
	s_waitcnt vmcnt(13)
	v_mul_f32_e32 v20, v20, v134
.LBB0_152:
	s_and_b64 vcc, exec, s[2:3]
	s_waitcnt vmcnt(13)
	ds_write_b32 v5, v20 offset:4752
	s_cbranch_vccnz .LBB0_154
	s_waitcnt vmcnt(12)
	v_mul_f32_e32 v18, v18, v135
.LBB0_154:
	s_and_b64 vcc, exec, s[2:3]
	s_waitcnt vmcnt(12)
	ds_write_b32 v5, v18 offset:5016
	s_cbranch_vccnz .LBB0_156
	s_waitcnt vmcnt(11)
	v_mul_f32_e32 v15, v15, v136
.LBB0_156:
	s_and_b64 vcc, exec, s[2:3]
	s_waitcnt vmcnt(11)
	ds_write_b32 v5, v15 offset:5280
	s_cbranch_vccnz .LBB0_158
	s_waitcnt vmcnt(10)
	v_mul_f32_e32 v12, v12, v137
.LBB0_158:
	s_and_b64 vcc, exec, s[2:3]
	s_waitcnt vmcnt(10)
	ds_write_b32 v5, v12 offset:5544
	s_cbranch_vccnz .LBB0_160
	s_waitcnt vmcnt(9)
	v_mul_f32_e32 v10, v10, v204
.LBB0_160:
	s_and_b64 vcc, exec, s[2:3]
	s_waitcnt vmcnt(9)
	ds_write_b32 v5, v10 offset:5808
	s_cbranch_vccnz .LBB0_162
	s_waitcnt vmcnt(8)
	v_mul_f32_e32 v8, v8, v205
.LBB0_162:
	s_and_b64 vcc, exec, s[2:3]
	s_waitcnt vmcnt(8)
	ds_write_b32 v5, v8 offset:6072
	s_cbranch_vccnz .LBB0_164
	s_waitcnt vmcnt(7)
	v_mul_f32_e32 v16, v16, v206
.LBB0_164:
	s_and_b64 vcc, exec, s[2:3]
	s_waitcnt vmcnt(7)
	ds_write_b32 v5, v16 offset:6336
	s_cbranch_vccnz .LBB0_166
	s_waitcnt vmcnt(6)
	v_mul_f32_e32 v13, v13, v207
.LBB0_166:
	s_and_b64 vcc, exec, s[2:3]
	s_waitcnt vmcnt(6)
	ds_write_b32 v5, v13 offset:6600
	s_cbranch_vccnz .LBB0_168
	s_waitcnt vmcnt(5)
	v_mul_f32_e32 v11, v11, v208
.LBB0_168:
	s_and_b64 vcc, exec, s[2:3]
	s_waitcnt vmcnt(5)
	ds_write_b32 v5, v11 offset:6864
	s_cbranch_vccnz .LBB0_170
	s_waitcnt vmcnt(4)
	v_mul_f32_e32 v9, v9, v209
.LBB0_170:
	s_and_b64 vcc, exec, s[2:3]
	s_waitcnt vmcnt(4)
	ds_write_b32 v5, v9 offset:7128
	s_cbranch_vccnz .LBB0_172
	s_waitcnt vmcnt(3)
	v_mul_f32_e32 v7, v7, v210
.LBB0_172:
	s_and_b64 vcc, exec, s[2:3]
	s_waitcnt vmcnt(3)
	ds_write_b32 v5, v7 offset:7392
	s_cbranch_vccnz .LBB0_174
	s_waitcnt vmcnt(2)
	v_mul_f32_e32 v6, v6, v211
.LBB0_174:
	s_and_b64 vcc, exec, s[2:3]
	s_waitcnt vmcnt(2)
	ds_write_b32 v5, v6 offset:7656
	s_cbranch_vccnz .LBB0_176
	s_waitcnt vmcnt(1)
	v_mul_f32_e32 v3, v3, v212
.LBB0_176:
	s_and_b64 vcc, exec, s[2:3]
	s_waitcnt vmcnt(1)
	ds_write_b32 v5, v3 offset:7920
	s_cbranch_vccnz .LBB0_178
	s_waitcnt vmcnt(0)
	v_mul_f32_e32 v2, v2, v213

; __device__ __forceinline__ void p0_item(const float* W, int ldw, const float* g, bf16* WT, int ldd, int row_off, int mat, bool split, LAS float* scr, int item, int nkb, int lane) {
;     const int rb = item / nkb, kb = item % nkb, k0 = 64 * kb, r0 = 32 * rb;
;     const int src = srcmap(mat, r0 + (lane & 31));
;     float wv[32];
;     const float* wp = W + (size_t)(k0 + (lane >> 5)) * ldw + (src >= 0 ? src : 0);
; #pragma unroll
;     for (int i = 0; i < 32; ++i) wv[i] = __builtin_nontemporal_load(wp + (size_t)(2 * i) * ldw);
;     const float gz = src >= 0 ? 1.f : 0.f;
; #pragma unroll
;     for (int i = 0; i < 32; ++i) { const int kk = 2 * i + (lane >> 5);
;         float v = wv[i] * gz; if (g) v *= g[k0 + kk];
;         scr[kk * 33 + (lane & 31)] = v; }
.LBB0_180:
	s_andn2_b64 vcc, exec, s[2:3]
	s_cbranch_vccnz .LBB0_246
	s_waitcnt vmcnt(9)
	v_mbcnt_lo_u32_b32 v4, -1, 0
	v_mbcnt_hi_u32_b32 v4, -1, v4
	s_and_b32 s57, s31, 0x3c0
	v_ashrrev_i32_e32 v27, 5, v4
	s_add_i32 s2, s45, 0xc00
	s_waitcnt vmcnt(8)
	v_add_u32_e32 v0, s57, v27
	s_and_b32 s56, s2, 0x1ffe0
	v_and_b32_e32 v5, 31, v4
	s_waitcnt lgkmcnt(0)
	v_ashrrev_i32_e32 v1, 31, v0
	v_readlane_b32 s48, v254, 59
	v_or_b32_e32 v6, s56, v5
	v_lshlrev_b64 v[2:3], 12, v[0:1]
	v_readlane_b32 s49, v254, 60
	v_lshlrev_b32_e32 v64, 2, v6
	s_movk_i32 s2, 0x2000
	v_lshl_add_u64 v[2:3], s[48:49], 0, v[2:3]
	v_lshl_add_u64 v[2:3], v[2:3], 0, v[64:65]
	v_add_co_u32_e32 v6, vcc, s2, v2
	s_movk_i32 s2, 0x4000
	s_nop 0
	v_addc_co_u32_e32 v7, vcc, 0, v3, vcc
	v_add_co_u32_e32 v8, vcc, s2, v2
	s_movk_i32 s2, 0x6000
	s_nop 0
	v_addc_co_u32_e32 v9, vcc, 0, v3, vcc
	v_add_co_u32_e32 v10, vcc, s2, v2
	s_mov_b32 s2, 0x8000
	s_nop 0
	v_addc_co_u32_e32 v11, vcc, 0, v3, vcc
	v_add_co_u32_e32 v12, vcc, s2, v2
	s_mov_b32 s2, 0xa000
	s_nop 0
	v_addc_co_u32_e32 v13, vcc, 0, v3, vcc
	v_add_co_u32_e32 v14, vcc, s2, v2
	s_mov_b32 s2, 0xc000
	s_nop 0
	v_addc_co_u32_e32 v15, vcc, 0, v3, vcc
	v_add_co_u32_e32 v16, vcc, s2, v2
	s_mov_b32 s2, 0xe000
	s_nop 0
	v_addc_co_u32_e32 v17, vcc, 0, v3, vcc
	v_add_co_u32_e32 v18, vcc, s2, v2
	s_mov_b32 s2, 0x10000
	s_nop 0
	v_addc_co_u32_e32 v19, vcc, 0, v3, vcc
	global_load_dword v36, v[2:3], off nt
	global_load_dword v35, v[6:7], off nt
	global_load_dword v34, v[8:9], off nt
	global_load_dword v32, v[10:11], off nt
	global_load_dword v30, v[12:13], off nt
	global_load_dword v28, v[14:15], off nt
	global_load_dword v24, v[16:17], off nt
	global_load_dword v21, v[18:19], off nt
	v_add_co_u32_e32 v6, vcc, s2, v2
	s_mov_b32 s2, 0x12000
	s_nop 0
	v_addc_co_u32_e32 v7, vcc, 0, v3, vcc
	v_add_co_u32_e32 v8, vcc, s2, v2
	s_mov_b32 s2, 0x14000
	s_nop 0
	v_addc_co_u32_e32 v9, vcc, 0, v3, vcc
	v_add_co_u32_e32 v10, vcc, s2, v2
	s_mov_b32 s2, 0x18000
	s_nop 0
	v_addc_co_u32_e32 v11, vcc, 0, v3, vcc
	v_add_co_u32_e32 v12, vcc, s75, v2
	v_readlane_b32 s48, v254, 37
	s_nop 0
	v_addc_co_u32_e32 v13, vcc, 0, v3, vcc
	v_add_co_u32_e32 v14, vcc, s2, v2
	s_mov_b32 s2, 0x1a000
	s_nop 0
	v_addc_co_u32_e32 v15, vcc, 0, v3, vcc
	v_add_co_u32_e32 v16, vcc, s2, v2
	s_mov_b32 s2, 0x1c000
	s_nop 0
	v_addc_co_u32_e32 v17, vcc, 0, v3, vcc
	v_add_co_u32_e32 v38, vcc, s2, v2
	s_mov_b32 s2, 0x1e000
	s_nop 0
	v_addc_co_u32_e32 v39, vcc, 0, v3, vcc
	v_add_co_u32_e32 v40, vcc, s2, v2
	s_mov_b32 s2, 0x20000
	s_nop 0
	v_addc_co_u32_e32 v41, vcc, 0, v3, vcc
	global_load_dword v33, v[6:7], off nt
	global_load_dword v31, v[8:9], off nt
	global_load_dword v29, v[10:11], off nt
	global_load_dword v25, v[12:13], off nt
	global_load_dword v22, v[14:15], off nt
	global_load_dword v19, v[16:17], off nt
	s_nop 0
	global_load_dword v17, v[38:39], off nt
	global_load_dword v14, v[40:41], off nt
	v_add_co_u32_e32 v6, vcc, s2, v2
	s_mov_b32 s2, 0x22000
	s_nop 0
	v_addc_co_u32_e32 v7, vcc, 0, v3, vcc
	v_add_co_u32_e32 v8, vcc, s2, v2
	s_mov_b32 s2, 0x24000
	s_nop 0
	v_addc_co_u32_e32 v9, vcc, 0, v3, vcc
	v_add_co_u32_e32 v10, vcc, s2, v2
	s_mov_b32 s2, 0x26000
	s_nop 0
	v_addc_co_u32_e32 v11, vcc, 0, v3, vcc
	v_add_co_u32_e32 v12, vcc, s2, v2
	s_mov_b32 s2, 0x28000
	s_nop 0
	v_addc_co_u32_e32 v13, vcc, 0, v3, vcc
	v_add_co_u32_e32 v38, vcc, s2, v2
	s_mov_b32 s2, 0x2a000
	s_nop 0
	v_addc_co_u32_e32 v39, vcc, 0, v3, vcc
	v_add_co_u32_e32 v40, vcc, s2, v2
	s_mov_b32 s2, 0x2e000
	s_nop 0
	v_addc_co_u32_e32 v41, vcc, 0, v3, vcc
	v_add_co_u32_e32 v42, vcc, s35, v2
	v_readlane_b32 s49, v254, 38
	s_nop 0
	v_addc_co_u32_e32 v43, vcc, 0, v3, vcc
	v_add_co_u32_e32 v44, vcc, s2, v2
	s_mov_b32 s2, 0x30000
	s_nop 0
	v_addc_co_u32_e32 v45, vcc, 0, v3, vcc
	global_load_dword v26, v[6:7], off nt
	global_load_dword v23, v[8:9], off nt
	global_load_dword v20, v[10:11], off nt
	global_load_dword v18, v[12:13], off nt
	global_load_dword v15, v[38:39], off nt
	s_nop 0
	global_load_dword v12, v[40:41], off nt
	global_load_dword v10, v[42:43], off nt
	global_load_dword v8, v[44:45], off nt
	v_add_co_u32_e32 v6, vcc, s2, v2
	s_mov_b32 s2, 0x32000
	s_nop 0
	v_addc_co_u32_e32 v7, vcc, 0, v3, vcc
	v_add_co_u32_e32 v38, vcc, s2, v2
	v_cndmask_b32_e64 v37, 0, 1, s[48:49]
	s_nop 0
	v_addc_co_u32_e32 v39, vcc, 0, v3, vcc
	v_add_co_u32_e32 v40, vcc, s97, v2
	v_cmp_ne_u32_e64 s[2:3], 1, v37
	s_nop 0
	v_addc_co_u32_e32 v41, vcc, 0, v3, vcc
	v_add_co_u32_e32 v42, vcc, s74, v2
	v_lshl_add_u64 v[0:1], v[0:1], 2, s[16:17]
	s_nop 0
	v_addc_co_u32_e32 v43, vcc, 0, v3, vcc
	v_add_co_u32_e32 v44, vcc, s96, v2
	v_readlane_b32 s50, v254, 61
	s_nop 0
	v_addc_co_u32_e32 v45, vcc, 0, v3, vcc
	v_add_co_u32_e32 v46, vcc, 0x3a000, v2
	v_readlane_b32 s51, v254, 62
	s_nop 0
	v_addc_co_u32_e32 v47, vcc, 0, v3, vcc
	v_add_co_u32_e32 v48, vcc, 0x3c000, v2
	s_nop 1
	v_addc_co_u32_e32 v49, vcc, 0, v3, vcc
	v_add_co_u32_e32 v50, vcc, 0x3e000, v2
	s_nop 1
	v_addc_co_u32_e32 v51, vcc, 0, v3, vcc
	global_load_dword v16, v[6:7], off nt
	global_load_dword v13, v[38:39], off nt
	global_load_dword v11, v[40:41], off nt
	global_load_dword v9, v[42:43], off nt
	s_nop 0
	global_load_dword v7, v[44:45], off nt
	global_load_dword v6, v[46:47], off nt
	global_load_dword v3, v[48:49], off nt
	global_load_dword v2, v[50:51], off nt
	s_andn2_b64 vcc, exec, s[48:49]
	s_cbranch_vccnz .Lp0g_2
	global_load_dword v56, v[0:1], off
	global_load_dword v57, v[0:1], off offset:8
	global_load_dword v58, v[0:1], off offset:16
	global_load_dword v59, v[0:1], off offset:24
	global_load_dword v60, v[0:1], off offset:32
	global_load_dword v61, v[0:1], off offset:40
	global_load_dword v62, v[0:1], off offset:48
	global_load_dword v63, v[0:1], off offset:56
	global_load_dword v78, v[0:1], off offset:64
	global_load_dword v79, v[0:1], off offset:72
	global_load_dword v80, v[0:1], off offset:80
	global_load_dword v81, v[0:1], off offset:88
	global_load_dword v82, v[0:1], off offset:96
	global_load_dword v83, v[0:1], off offset:104
	global_load_dword v84, v[0:1], off offset:112
	global_load_dword v85, v[0:1], off offset:120
	global_load_dword v98, v[0:1], off offset:128
	global_load_dword v103, v[0:1], off offset:136
	global_load_dword v134, v[0:1], off offset:144
	global_load_dword v135, v[0:1], off offset:152
	global_load_dword v136, v[0:1], off offset:160
	global_load_dword v137, v[0:1], off offset:168
	global_load_dword v204, v[0:1], off offset:176
	global_load_dword v205, v[0:1], off offset:184
	global_load_dword v206, v[0:1], off offset:192
	global_load_dword v207, v[0:1], off offset:200
	global_load_dword v208, v[0:1], off offset:208
	global_load_dword v209, v[0:1], off offset:216
	global_load_dword v210, v[0:1], off offset:224
	global_load_dword v211, v[0:1], off offset:232
	global_load_dword v212, v[0:1], off offset:240
	global_load_dword v213, v[0:1], off offset:248

; __device__ __forceinline__ void p0_item(const float* W, int ldw, const float* g, bf16* WT, int ldd, int row_off, int mat, bool split, LAS float* scr, int item, int nkb, int lane) {
;     const int rb = item / nkb, kb = item % nkb, k0 = 64 * kb, r0 = 32 * rb;
;     const int src = srcmap(mat, r0 + (lane & 31));
;     float wv[32];
;     const float* wp = W + (size_t)(k0 + (lane >> 5)) * ldw + (src >= 0 ? src : 0);
; #pragma unroll
;     for (int i = 0; i < 32; ++i) wv[i] = __builtin_nontemporal_load(wp + (size_t)(2 * i) * ldw);
;     const float gz = src >= 0 ? 1.f : 0.f;
; #pragma unroll
;     for (int i = 0; i < 32; ++i) { const int kk = 2 * i + (lane >> 5);
;         float v = wv[i] * gz; if (g) v *= g[k0 + kk];
;         scr[kk * 33 + (lane & 31)] = v; }
.LBB0_247:
	s_andn2_b64 vcc, exec, s[2:3]
	s_cbranch_vccnz .LBB0_313
	s_waitcnt vmcnt(9)
	v_mbcnt_lo_u32_b32 v4, -1, 0
	v_mbcnt_hi_u32_b32 v4, -1, v4
	s_and_b32 s57, s31, 0x3c0
	v_ashrrev_i32_e32 v28, 5, v4
	s_add_i32 s2, s45, 0x1000
	s_waitcnt vmcnt(8)
	v_add_u32_e32 v0, s57, v28
	s_and_b32 s56, s2, 0x1ffe0
	v_and_b32_e32 v5, 31, v4
	s_waitcnt lgkmcnt(0)
	v_ashrrev_i32_e32 v1, 31, v0
	v_or_b32_e32 v6, s56, v5
	v_lshlrev_b64 v[2:3], 12, v[0:1]
	v_lshl_add_u64 v[2:3], s[18:19], 0, v[2:3]
	v_lshlrev_b32_e32 v64, 2, v6
	v_lshl_add_u64 v[2:3], v[2:3], 0, v[64:65]
	s_movk_i32 s2, 0x2000
	v_add_co_u32_e32 v6, vcc, s2, v2
	s_movk_i32 s2, 0x4000
	s_nop 0
	v_addc_co_u32_e32 v7, vcc, 0, v3, vcc
	v_add_co_u32_e32 v8, vcc, s2, v2
	s_movk_i32 s2, 0x6000
	s_nop 0
	v_addc_co_u32_e32 v9, vcc, 0, v3, vcc
	v_add_co_u32_e32 v10, vcc, s2, v2
	s_mov_b32 s2, 0x8000
	s_nop 0
	v_addc_co_u32_e32 v11, vcc, 0, v3, vcc
	v_add_co_u32_e32 v12, vcc, s2, v2
	s_mov_b32 s2, 0xa000
	s_nop 0
	v_addc_co_u32_e32 v13, vcc, 0, v3, vcc
	v_add_co_u32_e32 v14, vcc, s2, v2
	s_mov_b32 s2, 0xc000
	s_nop 0
	v_addc_co_u32_e32 v15, vcc, 0, v3, vcc
	v_add_co_u32_e32 v16, vcc, s2, v2
	s_mov_b32 s2, 0xe000
	s_nop 0
	v_addc_co_u32_e32 v17, vcc, 0, v3, vcc
	v_add_co_u32_e32 v18, vcc, s2, v2
	s_mov_b32 s2, 0x10000
	s_nop 0
	v_addc_co_u32_e32 v19, vcc, 0, v3, vcc
	global_load_dword v36, v[2:3], off nt
	global_load_dword v35, v[6:7], off nt
	global_load_dword v34, v[8:9], off nt
	global_load_dword v32, v[10:11], off nt
	global_load_dword v30, v[12:13], off nt
	global_load_dword v27, v[14:15], off nt
	global_load_dword v24, v[16:17], off nt
	global_load_dword v21, v[18:19], off nt
	v_add_co_u32_e32 v6, vcc, s2, v2
	s_mov_b32 s2, 0x12000
	s_nop 0
	v_addc_co_u32_e32 v7, vcc, 0, v3, vcc
	v_add_co_u32_e32 v8, vcc, s2, v2
	s_mov_b32 s2, 0x14000
	s_nop 0
	v_addc_co_u32_e32 v9, vcc, 0, v3, vcc
	v_add_co_u32_e32 v10, vcc, s2, v2
	s_mov_b32 s2, 0x18000
	s_nop 0
	v_addc_co_u32_e32 v11, vcc, 0, v3, vcc
	v_add_co_u32_e32 v12, vcc, s75, v2
	v_cndmask_b32_e64 v37, 0, 1, s[76:77]
	s_nop 0
	v_addc_co_u32_e32 v13, vcc, 0, v3, vcc
	v_add_co_u32_e32 v14, vcc, s2, v2
	s_mov_b32 s2, 0x1a000
	s_nop 0
	v_addc_co_u32_e32 v15, vcc, 0, v3, vcc
	v_add_co_u32_e32 v16, vcc, s2, v2
	s_mov_b32 s2, 0x1c000
	s_nop 0
	v_addc_co_u32_e32 v17, vcc, 0, v3, vcc
	v_add_co_u32_e32 v38, vcc, s2, v2
	s_mov_b32 s2, 0x1e000
	s_nop 0
	v_addc_co_u32_e32 v39, vcc, 0, v3, vcc
	v_add_co_u32_e32 v40, vcc, s2, v2
	s_mov_b32 s2, 0x20000
	s_nop 0
	v_addc_co_u32_e32 v41, vcc, 0, v3, vcc
	global_load_dword v33, v[6:7], off nt
	global_load_dword v31, v[8:9], off nt
	global_load_dword v29, v[10:11], off nt
	global_load_dword v25, v[12:13], off nt
	global_load_dword v22, v[14:15], off nt
	global_load_dword v19, v[16:17], off nt
	s_nop 0
	global_load_dword v17, v[38:39], off nt
	global_load_dword v14, v[40:41], off nt
	v_add_co_u32_e32 v6, vcc, s2, v2
	s_mov_b32 s2, 0x22000
	s_nop 0
	v_addc_co_u32_e32 v7, vcc, 0, v3, vcc
	v_add_co_u32_e32 v8, vcc, s2, v2
	s_mov_b32 s2, 0x24000
	s_nop 0
	v_addc_co_u32_e32 v9, vcc, 0, v3, vcc
	v_add_co_u32_e32 v10, vcc, s2, v2
	s_mov_b32 s2, 0x26000
	s_nop 0
	v_addc_co_u32_e32 v11, vcc, 0, v3, vcc
	v_add_co_u32_e32 v12, vcc, s2, v2
	s_mov_b32 s2, 0x28000
	s_nop 0
	v_addc_co_u32_e32 v13, vcc, 0, v3, vcc
	v_add_co_u32_e32 v38, vcc, s2, v2
	s_mov_b32 s2, 0x2a000
	s_nop 0
	v_addc_co_u32_e32 v39, vcc, 0, v3, vcc
	v_add_co_u32_e32 v40, vcc, s2, v2
	s_mov_b32 s2, 0x2e000
	s_nop 0
	v_addc_co_u32_e32 v41, vcc, 0, v3, vcc
	v_add_co_u32_e32 v42, vcc, s35, v2
	v_lshl_add_u64 v[0:1], v[0:1], 2, s[14:15]
	s_nop 0
	v_addc_co_u32_e32 v43, vcc, 0, v3, vcc
	v_add_co_u32_e32 v44, vcc, s2, v2
	s_mov_b32 s2, 0x30000
	s_nop 0
	v_addc_co_u32_e32 v45, vcc, 0, v3, vcc
	global_load_dword v26, v[6:7], off nt
	global_load_dword v23, v[8:9], off nt
	global_load_dword v20, v[10:11], off nt
	global_load_dword v18, v[12:13], off nt
	global_load_dword v15, v[38:39], off nt
	s_nop 0
	global_load_dword v12, v[40:41], off nt
	global_load_dword v10, v[42:43], off nt
	global_load_dword v8, v[44:45], off nt
	v_add_co_u32_e32 v6, vcc, s2, v2
	s_mov_b32 s2, 0x32000
	s_nop 0
	v_addc_co_u32_e32 v7, vcc, 0, v3, vcc
	v_add_co_u32_e32 v38, vcc, s2, v2
	v_cmp_ne_u32_e64 s[2:3], 1, v37
	s_nop 0
	v_addc_co_u32_e32 v39, vcc, 0, v3, vcc
	v_add_co_u32_e32 v40, vcc, s97, v2
	s_nop 1
	v_addc_co_u32_e32 v41, vcc, 0, v3, vcc
	v_add_co_u32_e32 v42, vcc, s74, v2
	s_nop 1
	v_addc_co_u32_e32 v43, vcc, 0, v3, vcc
	v_add_co_u32_e32 v44, vcc, s96, v2
	s_nop 1
	v_addc_co_u32_e32 v45, vcc, 0, v3, vcc
	v_add_co_u32_e32 v46, vcc, 0x3a000, v2
	s_nop 1
	v_addc_co_u32_e32 v47, vcc, 0, v3, vcc
	v_add_co_u32_e32 v48, vcc, 0x3c000, v2
	s_nop 1
	v_addc_co_u32_e32 v49, vcc, 0, v3, vcc
	v_add_co_u32_e32 v50, vcc, 0x3e000, v2
	s_nop 1
	v_addc_co_u32_e32 v51, vcc, 0, v3, vcc
	global_load_dword v16, v[6:7], off nt
	global_load_dword v13, v[38:39], off nt
	global_load_dword v11, v[40:41], off nt
	global_load_dword v9, v[42:43], off nt
	s_nop 0
	global_load_dword v7, v[44:45], off nt
	global_load_dword v6, v[46:47], off nt
	global_load_dword v3, v[48:49], off nt
	global_load_dword v2, v[50:51], off nt
	s_andn2_b64 vcc, exec, s[76:77]
	s_cbranch_vccnz .Lp0g_3
	global_load_dword v56, v[0:1], off
	global_load_dword v57, v[0:1], off offset:8
	global_load_dword v58, v[0:1], off offset:16
	global_load_dword v59, v[0:1], off offset:24
	global_load_dword v60, v[0:1], off offset:32
	global_load_dword v61, v[0:1], off offset:40
	global_load_dword v62, v[0:1], off offset:48
	global_load_dword v63, v[0:1], off offset:56
	global_load_dword v78, v[0:1], off offset:64
	global_load_dword v79, v[0:1], off offset:72
	global_load_dword v80, v[0:1], off offset:80
	global_load_dword v81, v[0:1], off offset:88
	global_load_dword v82, v[0:1], off offset:96
	global_load_dword v83, v[0:1], off offset:104
	global_load_dword v84, v[0:1], off offset:112
	global_load_dword v85, v[0:1], off offset:120
	global_load_dword v98, v[0:1], off offset:128
	global_load_dword v103, v[0:1], off offset:136
	global_load_dword v134, v[0:1], off offset:144
	global_load_dword v135, v[0:1], off offset:152
	global_load_dword v136, v[0:1], off offset:160
	global_load_dword v137, v[0:1], off offset:168
	global_load_dword v204, v[0:1], off offset:176
	global_load_dword v205, v[0:1], off offset:184
	global_load_dword v206, v[0:1], off offset:192
	global_load_dword v207, v[0:1], off offset:200
	global_load_dword v208, v[0:1], off offset:208
	global_load_dword v209, v[0:1], off offset:216
	global_load_dword v210, v[0:1], off offset:224
	global_load_dword v211, v[0:1], off offset:232
	global_load_dword v212, v[0:1], off offset:240
	global_load_dword v213, v[0:1], off offset:248

; __device__ __forceinline__ void p0_item(const float* W, int ldw, const float* g, bf16* WT, int ldd, int row_off, int mat, bool split, LAS float* scr, int item, int nkb, int lane) {
;     ...
;     const float gz = src >= 0 ? 1.f : 0.f;
; #pragma unroll
;     for (int i = 0; i < 32; ++i) { const int kk = 2 * i + (lane >> 5);
;         float v = wv[i] * gz; if (g) v *= g[k0 + kk];
;         scr[kk * 33 + (lane & 31)] = v; }
.LBB0_250:
	v_lshl_add_u32 v5, v5, 2, s28
	v_mul_lo_u32 v28, v28, s26
	v_add_u32_e32 v5, v5, v28
	s_and_b64 vcc, exec, s[2:3]
	s_waitcnt vmcnt(31)
	ds_write_b32 v5, v36
	s_cbranch_vccnz .LBB0_252
	s_waitcnt vmcnt(30)
	v_mul_f32_e32 v35, v35, v57

; __device__ __forceinline__ void p0_item(const float* W, int ldw, const float* g, bf16* WT, int ldd, int row_off, int mat, bool split, LAS float* scr, int item, int nkb, int lane) {
;     ...
;     const float gz = src >= 0 ? 1.f : 0.f;
; #pragma unroll
;     for (int i = 0; i < 32; ++i) { const int kk = 2 * i + (lane >> 5);
;         float v = wv[i] * gz; if (g) v *= g[k0 + kk];
;         scr[kk * 33 + (lane & 31)] = v; }
.LBB0_258:
	s_and_b64 vcc, exec, s[2:3]
	s_waitcnt vmcnt(27)
	ds_write_b32 v5, v30 offset:1056
	s_cbranch_vccnz .LBB0_260
	s_waitcnt vmcnt(26)
	v_mul_f32_e32 v27, v27, v61
.LBB0_260:
	s_and_b64 vcc, exec, s[2:3]
	s_waitcnt vmcnt(26)
	ds_write_b32 v5, v27 offset:1320
	s_cbranch_vccnz .LBB0_262
	s_waitcnt vmcnt(25)
	v_mul_f32_e32 v24, v24, v62

; __device__ __forceinline__ void p0_item(const float* W, int ldw, const float* g, bf16* WT, int ldd, int row_off, int mat, bool split, LAS float* scr, int item, int nkb, int lane) {
;     const int rb = item / nkb, kb = item % nkb, k0 = 64 * kb, r0 = 32 * rb;
;     const int src = srcmap(mat, r0 + (lane & 31));
;     float wv[32];
;     const float* wp = W + (size_t)(k0 + (lane >> 5)) * ldw + (src >= 0 ? src : 0);
; #pragma unroll
;     for (int i = 0; i < 32; ++i) wv[i] = __builtin_nontemporal_load(wp + (size_t)(2 * i) * ldw);
;     const float gz = src >= 0 ? 1.f : 0.f;
; #pragma unroll
;     for (int i = 0; i < 32; ++i) { const int kk = 2 * i + (lane >> 5);
;         float v = wv[i] * gz; if (g) v *= g[k0 + kk];
;         scr[kk * 33 + (lane & 31)] = v; }
.LBB0_330:
	s_and_b32 s57, s31, 0x3c0
	v_ashrrev_i32_e32 v29, 5, v2
	v_add_u32_e32 v0, s57, v29
	v_mov_b64_e32 v[6:7], s[22:23]
	v_mad_i64_i32 v[6:7], s[2:3], v0, s27, v[6:7]
	s_waitcnt lgkmcnt(0)
	v_cmp_lt_i32_e64 s[2:3], -1, v1
	s_nop 1
	v_cndmask_b32_e64 v64, 0, v1, s[2:3]
	v_lshl_add_u64 v[6:7], v[64:65], 2, v[6:7]
	v_add_co_u32_e32 v8, vcc, 0x4000, v6
	v_ashrrev_i32_e32 v1, 31, v0
	s_nop 0
	v_addc_co_u32_e32 v9, vcc, 0, v7, vcc
	v_add_co_u32_e32 v10, vcc, 0x9000, v6
	v_cndmask_b32_e64 v4, 0, 1.0, s[2:3]
	s_nop 0
	v_addc_co_u32_e32 v11, vcc, 0, v7, vcc
	v_add_co_u32_e32 v12, vcc, 0xe000, v6
	v_lshl_add_u64 v[0:1], v[0:1], 2, s[20:21]
	s_nop 0
	v_addc_co_u32_e32 v13, vcc, 0, v7, vcc
	v_add_co_u32_e32 v14, vcc, 0x13000, v6
	s_nop 1
	v_addc_co_u32_e32 v15, vcc, 0, v7, vcc
	v_add_co_u32_e32 v16, vcc, 0x18000, v6
	s_nop 1
	v_addc_co_u32_e32 v17, vcc, 0, v7, vcc
	v_add_co_u32_e32 v18, vcc, 0x1d000, v6
	s_nop 1
	v_addc_co_u32_e32 v19, vcc, 0, v7, vcc
	v_add_co_u32_e32 v20, vcc, 0x22000, v6
	s_nop 1
	v_addc_co_u32_e32 v21, vcc, 0, v7, vcc
	global_load_dword v37, v[6:7], off nt
	global_load_dword v36, v[8:9], off offset:3616 nt
	global_load_dword v35, v[10:11], off offset:3136 nt
	global_load_dword v34, v[12:13], off offset:2656 nt
	global_load_dword v32, v[14:15], off offset:2176 nt
	global_load_dword v30, v[16:17], off offset:1696 nt
	global_load_dword v27, v[18:19], off offset:1216 nt
	global_load_dword v25, v[20:21], off offset:736 nt
	v_add_co_u32_e32 v8, vcc, 0x27000, v6
	s_waitcnt vmcnt(7)
	v_mul_f32_e32 v37, v37, v4
	v_addc_co_u32_e32 v9, vcc, 0, v7, vcc
	v_add_co_u32_e32 v10, vcc, 0x2b000, v6
	s_nop 1
	v_addc_co_u32_e32 v11, vcc, 0, v7, vcc
	v_add_co_u32_e32 v12, vcc, 0x30000, v6
	s_nop 1
	v_addc_co_u32_e32 v13, vcc, 0, v7, vcc
	v_add_co_u32_e32 v14, vcc, 0x35000, v6
	s_nop 1
	v_addc_co_u32_e32 v15, vcc, 0, v7, vcc
	v_add_co_u32_e32 v16, vcc, 0x3a000, v6
	s_nop 1
	v_addc_co_u32_e32 v17, vcc, 0, v7, vcc
	v_add_co_u32_e32 v18, vcc, 0x3f000, v6
	s_nop 1
	v_addc_co_u32_e32 v19, vcc, 0, v7, vcc
	v_add_co_u32_e32 v38, vcc, 0x44000, v6
	s_nop 1
	v_addc_co_u32_e32 v39, vcc, 0, v7, vcc
	v_add_co_u32_e32 v40, vcc, 0x49000, v6
	s_nop 1
	v_addc_co_u32_e32 v41, vcc, 0, v7, vcc
	global_load_dword v33, v[8:9], off offset:256 nt
	global_load_dword v31, v[10:11], off offset:3872 nt
	global_load_dword v28, v[12:13], off offset:3392 nt
	global_load_dword v26, v[14:15], off offset:2912 nt
	global_load_dword v23, v[16:17], off offset:2432 nt
	global_load_dword v21, v[18:19], off offset:1952 nt
	s_nop 0
	global_load_dword v19, v[38:39], off offset:1472 nt
	global_load_dword v17, v[40:41], off offset:992 nt
	v_add_co_u32_e32 v8, vcc, 0x4e000, v6
	s_nop 1
	v_addc_co_u32_e32 v9, vcc, 0, v7, vcc
	v_add_co_u32_e32 v10, vcc, 0x53000, v6
	s_nop 1
	v_addc_co_u32_e32 v11, vcc, 0, v7, vcc
	v_add_co_u32_e32 v12, vcc, 0x57000, v6
	s_nop 1
	v_addc_co_u32_e32 v13, vcc, 0, v7, vcc
	v_add_co_u32_e32 v14, vcc, 0x5c000, v6
	s_nop 1
	v_addc_co_u32_e32 v15, vcc, 0, v7, vcc
	v_add_co_u32_e32 v38, vcc, 0x61000, v6
	s_nop 1
	v_addc_co_u32_e32 v39, vcc, 0, v7, vcc
	v_add_co_u32_e32 v40, vcc, 0x66000, v6
	s_nop 1
	v_addc_co_u32_e32 v41, vcc, 0, v7, vcc
	v_add_co_u32_e32 v42, vcc, 0x6b000, v6
	s_nop 1
	v_addc_co_u32_e32 v43, vcc, 0, v7, vcc
	v_add_co_u32_e32 v44, vcc, 0x70000, v6
	s_nop 1
	v_addc_co_u32_e32 v45, vcc, 0, v7, vcc
	global_load_dword v24, v[8:9], off offset:512 nt
	global_load_dword v22, v[10:11], off offset:32 nt
	global_load_dword v20, v[12:13], off offset:3648 nt
	global_load_dword v18, v[14:15], off offset:3168 nt
	s_nop 0
	global_load_dword v15, v[38:39], off offset:2688 nt
	global_load_dword v13, v[40:41], off offset:2208 nt
	global_load_dword v11, v[42:43], off offset:1728 nt
	global_load_dword v9, v[44:45], off offset:1248 nt
	v_add_co_u32_e32 v38, vcc, 0x75000, v6
	s_nop 1
	v_addc_co_u32_e32 v39, vcc, 0, v7, vcc
	v_add_co_u32_e32 v40, vcc, 0x7a000, v6
	s_nop 1
	v_addc_co_u32_e32 v41, vcc, 0, v7, vcc
	v_add_co_u32_e32 v42, vcc, 0x7e000, v6
	s_nop 1
	v_addc_co_u32_e32 v43, vcc, 0, v7, vcc
	v_add_co_u32_e32 v44, vcc, 0x83000, v6
	s_nop 1
	v_addc_co_u32_e32 v45, vcc, 0, v7, vcc
	v_add_co_u32_e32 v46, vcc, 0x88000, v6
	s_nop 1
	v_addc_co_u32_e32 v47, vcc, 0, v7, vcc
	v_add_co_u32_e32 v48, vcc, 0x8d000, v6
	s_nop 1
	v_addc_co_u32_e32 v49, vcc, 0, v7, vcc
	v_add_co_u32_e32 v50, vcc, 0x92000, v6
	s_nop 1
	v_addc_co_u32_e32 v51, vcc, 0, v7, vcc
	v_add_co_u32_e32 v52, vcc, 0x97000, v6
	s_nop 1
	v_addc_co_u32_e32 v53, vcc, 0, v7, vcc
	global_load_dword v16, v[38:39], off offset:768 nt
	global_load_dword v14, v[40:41], off offset:288 nt
	global_load_dword v12, v[42:43], off offset:3904 nt
	global_load_dword v10, v[44:45], off offset:3424 nt
	global_load_dword v8, v[46:47], off offset:2944 nt
	global_load_dword v7, v[48:49], off offset:2464 nt
	global_load_dword v6, v[50:51], off offset:1984 nt
	global_load_dword v3, v[52:53], off offset:1504 nt
	v_cndmask_b32_e64 v38, 0, 1, s[70:71]
	v_cmp_ne_u32_e64 s[2:3], 1, v38
	s_andn2_b64 vcc, exec, s[70:71]
	s_cbranch_vccnz .Lp0g_4
	global_load_dword v56, v[0:1], off
	global_load_dword v57, v[0:1], off offset:8
	global_load_dword v58, v[0:1], off offset:16
	global_load_dword v59, v[0:1], off offset:24
	global_load_dword v60, v[0:1], off offset:32
	global_load_dword v61, v[0:1], off offset:40
	global_load_dword v62, v[0:1], off offset:48
	global_load_dword v63, v[0:1], off offset:56
	global_load_dword v78, v[0:1], off offset:64
	global_load_dword v79, v[0:1], off offset:72
	global_load_dword v80, v[0:1], off offset:80
	global_load_dword v81, v[0:1], off offset:88
	global_load_dword v82, v[0:1], off offset:96
	global_load_dword v83, v[0:1], off offset:104
	global_load_dword v84, v[0:1], off offset:112
	global_load_dword v85, v[0:1], off offset:120
	global_load_dword v98, v[0:1], off offset:128
	global_load_dword v103, v[0:1], off offset:136
	global_load_dword v134, v[0:1], off offset:144
	global_load_dword v135, v[0:1], off offset:152
	global_load_dword v136, v[0:1], off offset:160
	global_load_dword v137, v[0:1], off offset:168
	global_load_dword v204, v[0:1], off offset:176
	global_load_dword v205, v[0:1], off offset:184
	global_load_dword v206, v[0:1], off offset:192
	global_load_dword v207, v[0:1], off offset:200
	global_load_dword v208, v[0:1], off offset:208
	global_load_dword v209, v[0:1], off offset:216
	global_load_dword v210, v[0:1], off offset:224
	global_load_dword v211, v[0:1], off offset:232
	global_load_dword v212, v[0:1], off offset:240
	global_load_dword v213, v[0:1], off offset:248
; __device__ __forceinline__ void p0_item(const float* W, int ldw, const float* g, bf16* WT, int ldd, int row_off, int mat, bool split, LAS float* scr, int item, int nkb, int lane) {
;     ...
;     const float gz = src >= 0 ? 1.f : 0.f;
; #pragma unroll
;     for (int i = 0; i < 32; ++i) { const int kk = 2 * i + (lane >> 5);
;         float v = wv[i] * gz; if (g) v *= g[k0 + kk];
;         scr[kk * 33 + (lane & 31)] = v; }
.Lp0g_4:
	s_cbranch_vccnz .LBB0_332
	s_waitcnt vmcnt(31)
	v_mul_f32_e32 v37, v37, v56
.LBB0_332:
	v_lshl_add_u32 v5, v5, 2, s28
	v_mul_lo_u32 v29, v29, s26
	v_add_u32_e32 v5, v5, v29
	s_and_b64 vcc, exec, s[2:3]
	s_waitcnt vmcnt(30)
	v_mul_f32_e32 v29, v4, v36
	ds_write_b32 v5, v37
	s_cbranch_vccnz .LBB0_334
	s_waitcnt vmcnt(30)
	v_mul_f32_e32 v29, v29, v57
.LBB0_334:
	ds_write_b32 v5, v29 offset:264
	s_and_b64 vcc, exec, s[2:3]
	s_waitcnt vmcnt(29)
	v_mul_f32_e32 v29, v4, v35
	s_cbranch_vccnz .LBB0_336
	s_waitcnt vmcnt(29)
	v_mul_f32_e32 v29, v29, v58
.LBB0_336:
	ds_write_b32 v5, v29 offset:528
	s_and_b64 vcc, exec, s[2:3]
	s_waitcnt vmcnt(28)
	v_mul_f32_e32 v29, v4, v34
	s_cbranch_vccnz .LBB0_338
	s_waitcnt vmcnt(28)
	v_mul_f32_e32 v29, v29, v59
.LBB0_338:
	ds_write_b32 v5, v29 offset:792
	s_and_b64 vcc, exec, s[2:3]
	s_waitcnt vmcnt(27)
	v_mul_f32_e32 v29, v4, v32
	s_cbranch_vccnz .LBB0_340
	s_waitcnt vmcnt(27)
	v_mul_f32_e32 v29, v29, v60
.LBB0_340:
	ds_write_b32 v5, v29 offset:1056
	s_and_b64 vcc, exec, s[2:3]
	s_waitcnt vmcnt(26)
	v_mul_f32_e32 v29, v4, v30
	s_cbranch_vccnz .LBB0_342
	s_waitcnt vmcnt(26)
	v_mul_f32_e32 v29, v29, v61
.LBB0_342:
	s_and_b64 vcc, exec, s[2:3]
	s_waitcnt vmcnt(25)
	v_mul_f32_e32 v27, v4, v27
	ds_write_b32 v5, v29 offset:1320
	s_cbranch_vccnz .LBB0_344
	s_waitcnt vmcnt(25)
	v_mul_f32_e32 v27, v27, v62
.LBB0_344:
	s_and_b64 vcc, exec, s[2:3]
	s_waitcnt vmcnt(24)
	v_mul_f32_e32 v25, v4, v25
	ds_write_b32 v5, v27 offset:1584
	s_cbranch_vccnz .LBB0_346
	s_waitcnt vmcnt(24)
	v_mul_f32_e32 v25, v25, v63
.LBB0_346:
	ds_write_b32 v5, v25 offset:1848
	s_and_b64 vcc, exec, s[2:3]
	s_waitcnt vmcnt(23)
	v_mul_f32_e32 v25, v4, v33
	s_cbranch_vccnz .LBB0_348
	s_waitcnt vmcnt(23)
	v_mul_f32_e32 v25, v25, v78
.LBB0_348:
	ds_write_b32 v5, v25 offset:2112
	s_and_b64 vcc, exec, s[2:3]
	s_waitcnt vmcnt(22)
	v_mul_f32_e32 v25, v4, v31
	s_cbranch_vccnz .LBB0_350
	s_waitcnt vmcnt(22)
	v_mul_f32_e32 v25, v25, v79
.LBB0_350:
	ds_write_b32 v5, v25 offset:2376
	s_and_b64 vcc, exec, s[2:3]
	s_waitcnt vmcnt(21)
	v_mul_f32_e32 v25, v4, v28
	s_cbranch_vccnz .LBB0_352
	s_waitcnt vmcnt(21)
	v_mul_f32_e32 v25, v25, v80
.LBB0_352:
	ds_write_b32 v5, v25 offset:2640
	s_and_b64 vcc, exec, s[2:3]
	s_waitcnt vmcnt(20)
	v_mul_f32_e32 v25, v4, v26
	s_cbranch_vccnz .LBB0_354
	s_waitcnt vmcnt(20)
	v_mul_f32_e32 v25, v25, v81
.LBB0_354:
	s_and_b64 vcc, exec, s[2:3]
	s_waitcnt vmcnt(19)
	v_mul_f32_e32 v23, v4, v23
	ds_write_b32 v5, v25 offset:2904
	s_cbranch_vccnz .LBB0_356
	s_waitcnt vmcnt(19)
	v_mul_f32_e32 v23, v23, v82
.LBB0_356:
	s_and_b64 vcc, exec, s[2:3]
	s_waitcnt vmcnt(18)
	v_mul_f32_e32 v21, v4, v21
	ds_write_b32 v5, v23 offset:3168
	s_cbranch_vccnz .LBB0_358
	s_waitcnt vmcnt(18)
	v_mul_f32_e32 v21, v21, v83
.LBB0_358:
	s_and_b64 vcc, exec, s[2:3]
	s_waitcnt vmcnt(17)
	v_mul_f32_e32 v19, v4, v19
	ds_write_b32 v5, v21 offset:3432
	s_cbranch_vccnz .LBB0_360
	s_waitcnt vmcnt(17)
	v_mul_f32_e32 v19, v19, v84
.LBB0_360:
	s_and_b64 vcc, exec, s[2:3]
	s_waitcnt vmcnt(16)
	v_mul_f32_e32 v17, v4, v17
	ds_write_b32 v5, v19 offset:3696
	s_cbranch_vccnz .LBB0_362
	s_waitcnt vmcnt(16)
	v_mul_f32_e32 v17, v17, v85
.LBB0_362:
	ds_write_b32 v5, v17 offset:3960
	s_and_b64 vcc, exec, s[2:3]
	s_waitcnt vmcnt(15)
	v_mul_f32_e32 v17, v4, v24
	s_cbranch_vccnz .LBB0_364
	s_waitcnt vmcnt(15)
	v_mul_f32_e32 v17, v17, v98
.LBB0_364:
	ds_write_b32 v5, v17 offset:4224
	s_and_b64 vcc, exec, s[2:3]
	s_waitcnt vmcnt(14)
	v_mul_f32_e32 v17, v4, v22
	s_cbranch_vccnz .LBB0_366
	s_waitcnt vmcnt(14)
	v_mul_f32_e32 v17, v17, v103
.LBB0_366:
	ds_write_b32 v5, v17 offset:4488
	s_and_b64 vcc, exec, s[2:3]
	s_waitcnt vmcnt(13)
	v_mul_f32_e32 v17, v4, v20
	s_cbranch_vccnz .LBB0_368
	s_waitcnt vmcnt(13)
	v_mul_f32_e32 v17, v17, v134
.LBB0_368:
	ds_write_b32 v5, v17 offset:4752
	s_and_b64 vcc, exec, s[2:3]
	s_waitcnt vmcnt(12)
	v_mul_f32_e32 v17, v4, v18
	s_cbranch_vccnz .LBB0_370
	s_waitcnt vmcnt(12)
	v_mul_f32_e32 v17, v17, v135
.LBB0_370:
	s_and_b64 vcc, exec, s[2:3]
	s_waitcnt vmcnt(11)
	v_mul_f32_e32 v15, v4, v15
	ds_write_b32 v5, v17 offset:5016
	s_cbranch_vccnz .LBB0_372
	s_waitcnt vmcnt(11)
	v_mul_f32_e32 v15, v15, v136
.LBB0_372:
	s_and_b64 vcc, exec, s[2:3]
	s_waitcnt vmcnt(10)
	v_mul_f32_e32 v13, v4, v13
	ds_write_b32 v5, v15 offset:5280
	s_cbranch_vccnz .LBB0_374
	s_waitcnt vmcnt(10)
	v_mul_f32_e32 v13, v13, v137
.LBB0_374:
	s_and_b64 vcc, exec, s[2:3]
	s_waitcnt vmcnt(9)
	v_mul_f32_e32 v11, v4, v11
	ds_write_b32 v5, v13 offset:5544
	s_cbranch_vccnz .LBB0_376
	s_waitcnt vmcnt(9)
	v_mul_f32_e32 v11, v11, v204
.LBB0_376:
	s_and_b64 vcc, exec, s[2:3]
	s_waitcnt vmcnt(8)
	v_mul_f32_e32 v9, v4, v9
	ds_write_b32 v5, v11 offset:5808
	s_cbranch_vccnz .LBB0_378
	s_waitcnt vmcnt(8)
	v_mul_f32_e32 v9, v9, v205
.LBB0_378:
	ds_write_b32 v5, v9 offset:6072
	s_and_b64 vcc, exec, s[2:3]
	s_waitcnt vmcnt(7)
	v_mul_f32_e32 v9, v4, v16
	s_cbranch_vccnz .LBB0_380
	s_waitcnt vmcnt(7)
	v_mul_f32_e32 v9, v9, v206
.LBB0_380:
	ds_write_b32 v5, v9 offset:6336
	s_and_b64 vcc, exec, s[2:3]
	s_waitcnt vmcnt(6)
	v_mul_f32_e32 v9, v4, v14
	s_cbranch_vccnz .LBB0_382
	s_waitcnt vmcnt(6)
	v_mul_f32_e32 v9, v9, v207
.LBB0_382:
	ds_write_b32 v5, v9 offset:6600
	s_and_b64 vcc, exec, s[2:3]
	s_waitcnt vmcnt(5)
	v_mul_f32_e32 v9, v4, v12
	s_cbranch_vccnz .LBB0_384
	s_waitcnt vmcnt(5)
	v_mul_f32_e32 v9, v9, v208
.LBB0_384:
	ds_write_b32 v5, v9 offset:6864
	s_and_b64 vcc, exec, s[2:3]
	s_waitcnt vmcnt(4)
	v_mul_f32_e32 v9, v4, v10
	s_cbranch_vccnz .LBB0_386
	s_waitcnt vmcnt(4)
	v_mul_f32_e32 v9, v9, v209
.LBB0_386:
	s_and_b64 vcc, exec, s[2:3]
	s_waitcnt vmcnt(3)
	v_mul_f32_e32 v8, v4, v8
	ds_write_b32 v5, v9 offset:7128
	s_cbranch_vccnz .LBB0_388
	s_waitcnt vmcnt(3)
	v_mul_f32_e32 v8, v8, v210
.LBB0_388:
	s_and_b64 vcc, exec, s[2:3]
	s_waitcnt vmcnt(2)
	v_mul_f32_e32 v7, v4, v7
	ds_write_b32 v5, v8 offset:7392
	s_cbranch_vccnz .LBB0_390
	s_waitcnt vmcnt(2)
	v_mul_f32_e32 v7, v7, v211
.LBB0_390:
	s_and_b64 vcc, exec, s[2:3]
	s_waitcnt vmcnt(1)
	v_mul_f32_e32 v6, v4, v6
	ds_write_b32 v5, v7 offset:7656
	s_cbranch_vccnz .LBB0_392
	s_waitcnt vmcnt(1)
	v_mul_f32_e32 v6, v6, v212
.LBB0_392:
	s_and_b64 vcc, exec, s[2:3]
	s_waitcnt vmcnt(0)
	v_mul_f32_e32 v3, v4, v3
	ds_write_b32 v5, v6 offset:7920
	s_cbranch_vccnz .LBB0_394
	s_waitcnt vmcnt(0)
	v_mul_f32_e32 v3, v3, v213

; __device__ __forceinline__ void p0_item(const float* W, int ldw, const float* g, bf16* WT, int ldd, int row_off, int mat, bool split, LAS float* scr, int item, int nkb, int lane) {
;     const int rb = item / nkb, kb = item % nkb, k0 = 64 * kb, r0 = 32 * rb;
;     const int src = srcmap(mat, r0 + (lane & 31));
;     float wv[32];
;     const float* wp = W + (size_t)(k0 + (lane >> 5)) * ldw + (src >= 0 ? src : 0);
; #pragma unroll
;     for (int i = 0; i < 32; ++i) wv[i] = __builtin_nontemporal_load(wp + (size_t)(2 * i) * ldw);
;     const float gz = src >= 0 ? 1.f : 0.f;
; #pragma unroll
;     for (int i = 0; i < 32; ++i) { const int kk = 2 * i + (lane >> 5);
;         float v = wv[i] * gz; if (g) v *= g[k0 + kk];
;         scr[kk * 33 + (lane & 31)] = v; }
.LBB0_409:
	v_ashrrev_i32_e32 v29, 5, v2
	s_lshl_b32 s57, s57, 10
	v_subrev_u32_e32 v0, s57, v29
	v_add_u32_e32 v0, s31, v0
	v_mov_b64_e32 v[6:7], s[22:23]
	v_mad_i64_i32 v[6:7], s[2:3], v0, s27, v[6:7]
	s_waitcnt lgkmcnt(0)
	v_cmp_lt_i32_e64 s[2:3], -1, v1
	s_nop 1
	v_cndmask_b32_e64 v64, 0, v1, s[2:3]
	v_lshl_add_u64 v[6:7], v[64:65], 2, v[6:7]
	v_add_co_u32_e32 v8, vcc, 0x4000, v6
	v_ashrrev_i32_e32 v1, 31, v0
	s_nop 0
	v_addc_co_u32_e32 v9, vcc, 0, v7, vcc
	v_add_co_u32_e32 v10, vcc, 0x9000, v6
	v_cndmask_b32_e64 v4, 0, 1.0, s[2:3]
	s_nop 0
	v_addc_co_u32_e32 v11, vcc, 0, v7, vcc
	v_add_co_u32_e32 v12, vcc, 0xe000, v6
	v_lshl_add_u64 v[0:1], v[0:1], 2, s[20:21]
	s_nop 0
	v_addc_co_u32_e32 v13, vcc, 0, v7, vcc
	v_add_co_u32_e32 v14, vcc, 0x13000, v6
	s_nop 1
	v_addc_co_u32_e32 v15, vcc, 0, v7, vcc
	v_add_co_u32_e32 v16, vcc, 0x18000, v6
	s_nop 1
	v_addc_co_u32_e32 v17, vcc, 0, v7, vcc
	v_add_co_u32_e32 v18, vcc, 0x1d000, v6
	s_nop 1
	v_addc_co_u32_e32 v19, vcc, 0, v7, vcc
	v_add_co_u32_e32 v20, vcc, 0x22000, v6
	s_nop 1
	v_addc_co_u32_e32 v21, vcc, 0, v7, vcc
	global_load_dword v37, v[6:7], off nt
	global_load_dword v36, v[8:9], off offset:3616 nt
	global_load_dword v35, v[10:11], off offset:3136 nt
	global_load_dword v34, v[12:13], off offset:2656 nt
	global_load_dword v32, v[14:15], off offset:2176 nt
	global_load_dword v30, v[16:17], off offset:1696 nt
	global_load_dword v27, v[18:19], off offset:1216 nt
	global_load_dword v25, v[20:21], off offset:736 nt
	v_add_co_u32_e32 v8, vcc, 0x27000, v6
	s_waitcnt vmcnt(7)
	v_mul_f32_e32 v37, v37, v4
	v_addc_co_u32_e32 v9, vcc, 0, v7, vcc
	v_add_co_u32_e32 v10, vcc, 0x2b000, v6
	s_nop 1
	v_addc_co_u32_e32 v11, vcc, 0, v7, vcc
	v_add_co_u32_e32 v12, vcc, 0x30000, v6
	s_nop 1
	v_addc_co_u32_e32 v13, vcc, 0, v7, vcc
	v_add_co_u32_e32 v14, vcc, 0x35000, v6
	s_nop 1
	v_addc_co_u32_e32 v15, vcc, 0, v7, vcc
	v_add_co_u32_e32 v16, vcc, 0x3a000, v6
	s_nop 1
	v_addc_co_u32_e32 v17, vcc, 0, v7, vcc
	v_add_co_u32_e32 v18, vcc, 0x3f000, v6
	s_nop 1
	v_addc_co_u32_e32 v19, vcc, 0, v7, vcc
	v_add_co_u32_e32 v38, vcc, 0x44000, v6
	s_nop 1
	v_addc_co_u32_e32 v39, vcc, 0, v7, vcc
	v_add_co_u32_e32 v40, vcc, 0x49000, v6
	s_nop 1
	v_addc_co_u32_e32 v41, vcc, 0, v7, vcc
	global_load_dword v33, v[8:9], off offset:256 nt
	global_load_dword v31, v[10:11], off offset:3872 nt
	global_load_dword v28, v[12:13], off offset:3392 nt
	global_load_dword v26, v[14:15], off offset:2912 nt
	global_load_dword v23, v[16:17], off offset:2432 nt
	global_load_dword v21, v[18:19], off offset:1952 nt
	s_nop 0
	global_load_dword v19, v[38:39], off offset:1472 nt
	global_load_dword v17, v[40:41], off offset:992 nt
	v_add_co_u32_e32 v8, vcc, 0x4e000, v6
	s_nop 1
	v_addc_co_u32_e32 v9, vcc, 0, v7, vcc
	v_add_co_u32_e32 v10, vcc, 0x53000, v6
	s_nop 1
	v_addc_co_u32_e32 v11, vcc, 0, v7, vcc
	v_add_co_u32_e32 v12, vcc, 0x57000, v6
	s_nop 1
	v_addc_co_u32_e32 v13, vcc, 0, v7, vcc
	v_add_co_u32_e32 v14, vcc, 0x5c000, v6
	s_nop 1
	v_addc_co_u32_e32 v15, vcc, 0, v7, vcc
	v_add_co_u32_e32 v38, vcc, 0x61000, v6
	s_nop 1
	v_addc_co_u32_e32 v39, vcc, 0, v7, vcc
	v_add_co_u32_e32 v40, vcc, 0x66000, v6
	s_nop 1
	v_addc_co_u32_e32 v41, vcc, 0, v7, vcc
	v_add_co_u32_e32 v42, vcc, 0x6b000, v6
	s_nop 1
	v_addc_co_u32_e32 v43, vcc, 0, v7, vcc
	v_add_co_u32_e32 v44, vcc, 0x70000, v6
	s_nop 1
	v_addc_co_u32_e32 v45, vcc, 0, v7, vcc
	global_load_dword v24, v[8:9], off offset:512 nt
	global_load_dword v22, v[10:11], off offset:32 nt
	global_load_dword v20, v[12:13], off offset:3648 nt
	global_load_dword v18, v[14:15], off offset:3168 nt
	s_nop 0
	global_load_dword v15, v[38:39], off offset:2688 nt
	global_load_dword v13, v[40:41], off offset:2208 nt
	global_load_dword v11, v[42:43], off offset:1728 nt
	global_load_dword v9, v[44:45], off offset:1248 nt
	v_add_co_u32_e32 v38, vcc, 0x75000, v6
	s_nop 1
	v_addc_co_u32_e32 v39, vcc, 0, v7, vcc
	v_add_co_u32_e32 v40, vcc, 0x7a000, v6
	s_nop 1
	v_addc_co_u32_e32 v41, vcc, 0, v7, vcc
	v_add_co_u32_e32 v42, vcc, 0x7e000, v6
	s_nop 1
	v_addc_co_u32_e32 v43, vcc, 0, v7, vcc
	v_add_co_u32_e32 v44, vcc, 0x83000, v6
	s_nop 1
	v_addc_co_u32_e32 v45, vcc, 0, v7, vcc
	v_add_co_u32_e32 v46, vcc, 0x88000, v6
	s_nop 1
	v_addc_co_u32_e32 v47, vcc, 0, v7, vcc
	v_add_co_u32_e32 v48, vcc, 0x8d000, v6
	s_nop 1
	v_addc_co_u32_e32 v49, vcc, 0, v7, vcc
	v_add_co_u32_e32 v50, vcc, 0x92000, v6
	s_nop 1
	v_addc_co_u32_e32 v51, vcc, 0, v7, vcc
	v_add_co_u32_e32 v52, vcc, 0x97000, v6
	s_nop 1
	v_addc_co_u32_e32 v53, vcc, 0, v7, vcc
	global_load_dword v16, v[38:39], off offset:768 nt
	global_load_dword v14, v[40:41], off offset:288 nt
	global_load_dword v12, v[42:43], off offset:3904 nt
	global_load_dword v10, v[44:45], off offset:3424 nt
	global_load_dword v8, v[46:47], off offset:2944 nt
	global_load_dword v7, v[48:49], off offset:2464 nt
	global_load_dword v6, v[50:51], off offset:1984 nt
	global_load_dword v3, v[52:53], off offset:1504 nt
	v_cndmask_b32_e64 v38, 0, 1, s[70:71]
	v_cmp_ne_u32_e64 s[2:3], 1, v38
	s_andn2_b64 vcc, exec, s[70:71]
	s_cbranch_vccnz .Lp0g_5
	global_load_dword v56, v[0:1], off
	global_load_dword v57, v[0:1], off offset:8
	global_load_dword v58, v[0:1], off offset:16
	global_load_dword v59, v[0:1], off offset:24
	global_load_dword v60, v[0:1], off offset:32
	global_load_dword v61, v[0:1], off offset:40
	global_load_dword v62, v[0:1], off offset:48
	global_load_dword v63, v[0:1], off offset:56
	global_load_dword v78, v[0:1], off offset:64
	global_load_dword v79, v[0:1], off offset:72
	global_load_dword v80, v[0:1], off offset:80
	global_load_dword v81, v[0:1], off offset:88
	global_load_dword v82, v[0:1], off offset:96
	global_load_dword v83, v[0:1], off offset:104
	global_load_dword v84, v[0:1], off offset:112
	global_load_dword v85, v[0:1], off offset:120
	global_load_dword v98, v[0:1], off offset:128
	global_load_dword v103, v[0:1], off offset:136
	global_load_dword v134, v[0:1], off offset:144
	global_load_dword v135, v[0:1], off offset:152
	global_load_dword v136, v[0:1], off offset:160
	global_load_dword v137, v[0:1], off offset:168
	global_load_dword v204, v[0:1], off offset:176
	global_load_dword v205, v[0:1], off offset:184
	global_load_dword v206, v[0:1], off offset:192
	global_load_dword v207, v[0:1], off offset:200
	global_load_dword v208, v[0:1], off offset:208
	global_load_dword v209, v[0:1], off offset:216
	global_load_dword v210, v[0:1], off offset:224
	global_load_dword v211, v[0:1], off offset:232
	global_load_dword v212, v[0:1], off offset:240
	global_load_dword v213, v[0:1], off offset:248

; __device__ __forceinline__ void p0_item(const float* W, int ldw, const float* g, bf16* WT, int ldd, int row_off, int mat, bool split, LAS float* scr, int item, int nkb, int lane) {
;     ...
;     const float gz = src >= 0 ? 1.f : 0.f;
; #pragma unroll
;     for (int i = 0; i < 32; ++i) { const int kk = 2 * i + (lane >> 5);
;         float v = wv[i] * gz; if (g) v *= g[k0 + kk];
;         scr[kk * 33 + (lane & 31)] = v; }
.LBB0_471:
	s_and_b64 vcc, exec, s[2:3]
	s_waitcnt vmcnt(0)
	v_mul_f32_e32 v3, v4, v3
	ds_write_b32 v5, v6 offset:7920
	s_cbranch_vccnz .LBB0_32
	s_waitcnt vmcnt(0)
	v_mul_f32_e32 v3, v3, v213
	s_branch .LBB0_32
